# shfl_xor butterflies of the mixers (ds_bpermute + LDS wait per step) converted to DPP / permlane-swap moves, counted LDS waits adjusted
# speedup vs baseline: 1.1960x; 1.0108x over previous
.LBB0_428:
	s_or_b64 exec, exec, s[0:1]
	s_movk_i32 s0, 0x100
	v_ashrrev_i32_e32 v158, 6, v150
	v_cmp_gt_u32_e64 s[38:39], s0, v150
	s_movk_i32 s0, 0xff
	v_and_b32_e32 v154, 3, v158
	s_waitcnt lgkmcnt(0)
	s_barrier
	v_cmp_lt_u32_e64 s[40:41], s0, v150
	s_lshl_b32 s0, s50, 6
	v_lshlrev_b32_e32 v155, 2, v152
	v_or_b32_e32 v0, s0, v149
	v_lshlrev_b32_e32 v153, 4, v154
	v_lshlrev_b32_e32 v2, 2, v0
	v_lshlrev_b32_e32 v164, 1, v149
	v_or_b32_e32 v151, v153, v149
	v_or_b32_e32 v148, v153, v155
	v_lshl_add_u32 v157, v149, 2, 0
	v_add_lshl_u32 v159, v149, s0, 2
	s_and_saveexec_b64 s[0:1], s[40:41]
	s_xor_b64 s[42:43], exec, s[0:1]
	s_cbranch_execz .LBB0_430
	v_readlane_b32 s80, v252, 18
	v_readlane_b32 s94, v252, 32
	v_readlane_b32 s95, v252, 33
	v_mul_u32_u24_e32 v0, 0x190, v151
	v_and_b32_e32 v3, 48, v150
	v_readlane_b32 s0, v254, 52
	v_readlane_b32 s81, v252, 19
	v_readlane_b32 s82, v252, 20
	global_load_dword v74, v2, s[94:95]
	v_readlane_b32 s83, v252, 21
	v_readlane_b32 s84, v252, 22
	v_readlane_b32 s85, v252, 23
	v_readlane_b32 s86, v252, 24
	v_readlane_b32 s87, v252, 25
	v_readlane_b32 s88, v252, 26
	v_readlane_b32 s89, v252, 27
	v_readlane_b32 s90, v252, 28
	v_readlane_b32 s91, v252, 29
	v_readlane_b32 s92, v252, 30
	v_readlane_b32 s93, v252, 31
	v_add3_u32 v0, s0, v0, v3
	s_mov_b64 s[62:63], s[94:95]
	v_readlane_b32 s80, v252, 35
	ds_read_b128 v[64:67], v0 offset:128
	v_readlane_b32 s84, v252, 39
	v_readlane_b32 s85, v252, 40
	v_readlane_b32 s86, v252, 41
	v_readlane_b32 s87, v252, 42
	v_readlane_b32 s88, v252, 43
	v_readlane_b32 s89, v252, 44
	v_readlane_b32 s90, v252, 45
	v_readlane_b32 s91, v252, 46
	v_readlane_b32 s92, v252, 47
	v_readlane_b32 s93, v252, 48
	s_mov_b64 s[52:53], s[84:85]
	s_mov_b64 s[54:55], s[86:87]
	global_load_dword v0, v2, s[52:53]
	global_load_dword v76, v2, s[54:55]
	v_mul_u32_u24_e32 v3, 0x300, v148
	v_add_u32_e32 v100, 0xc400, v157
	v_add_u32_e32 v102, 0xcc00, v157
	v_add_u32_e32 v103, 0xd000, v157
	v_add3_u32 v117, 0, v3, v164
	ds_read2_b32 v[72:73], v100 offset0:192 offset1:208
	ds_read2_b32 v[78:79], v102 offset0:64 offset1:80
	ds_read2_b32 v[84:85], v103 offset0:192 offset1:208
	ds_read_u16 v87, v117 offset:896
	ds_read_u16 v93, v117 offset:1664
	ds_read_u16 v3, v117 offset:2432
	ds_read_u16 v95, v117 offset:3200
	ds_read_u16 v99, v117 offset:3968
	s_waitcnt lgkmcnt(8)
	v_mfma_f32_16x16x32_bf16 v[68:71], v[64:67], v[24:27], 0
	s_waitcnt lgkmcnt(5)
	v_mov_b32_e32 v168, v85
	s_waitcnt lgkmcnt(2)
	v_lshlrev_b32_e32 v86, 16, v3
	v_lshlrev_b32_e32 v142, 16, v93
	s_waitcnt lgkmcnt(1)
	v_lshlrev_b32_e32 v143, 16, v95
	s_mov_b32 s4, 0x2b8cbccc
	s_mov_b32 s10, 0x45800000
	v_readlane_b32 s81, v252, 36
	v_readlane_b32 s82, v252, 37
	v_readlane_b32 s83, v252, 38
	v_readlane_b32 s94, v252, 49
	v_readlane_b32 s95, v252, 50
	s_mov_b64 s[56:57], s[88:89]
	s_mov_b64 s[58:59], s[90:91]
	s_mov_b64 s[60:61], s[92:93]
	s_waitcnt vmcnt(2)
	v_add_f32_e32 v2, v74, v68
	v_add_f32_e32 v3, v74, v69
	v_mul_f32_e32 v2, 0xbfb8aa3b, v2
	v_mul_f32_e32 v3, 0xbfb8aa3b, v3
	v_exp_f32_e32 v2, v2
	v_exp_f32_e32 v3, v3
	s_nop 0
	v_pk_add_f32 v[2:3], v[2:3], 1.0 op_sel_hi:[1,0]
	v_rcp_f32_e32 v3, v3
	v_div_scale_f32 v68, s[0:1], v2, v2, 1.0
	v_rcp_f32_e32 v69, v68
	s_nop 0
	v_fma_f32 v75, -v68, v69, 1.0
	v_fmac_f32_e32 v69, v75, v69
	v_div_scale_f32 v75, vcc, 1.0, v2, 1.0
	v_mul_f32_e32 v77, v75, v69
	v_fma_f32 v80, -v68, v77, v75
	v_fmac_f32_e32 v77, v80, v69
	global_load_dword v81, v159, s[62:63] offset:64
	global_load_dword v92, v159, s[52:53] offset:64
	global_load_dword v80, v159, s[54:55] offset:64
	v_fma_f32 v68, -v68, v77, v75
	v_div_fmas_f32 v68, v68, v69, v77
	v_div_fixup_f32 v2, v68, v2, 1.0
	v_pk_add_f32 v[68:69], v[2:3], -1.0 op_sel_hi:[1,0]
	ds_read_u16 v109, v117 offset:128
	ds_read_u16 v113, v117 offset:160
	ds_read_u16 v115, v117 offset:928
	ds_read_u16 v118, v117 offset:1696
	s_waitcnt vmcnt(3)
	v_pk_fma_f32 v[88:89], v[76:77], v[68:69], 1.0 op_sel_hi:[0,1,0]
	v_add_f32_e32 v68, v74, v70
	v_add_f32_e32 v69, v74, v71
	v_mul_f32_e32 v68, 0xbfb8aa3b, v68
	v_mul_f32_e32 v69, 0xbfb8aa3b, v69
	v_exp_f32_e32 v68, v68
	v_exp_f32_e32 v69, v69
	ds_read_u16 v82, v117 offset:2464
	ds_read_u16 v119, v117 offset:3232
	ds_read_u16 v120, v117 offset:4000
	v_pk_add_f32 v[68:69], v[68:69], 1.0 op_sel_hi:[1,0]
	s_waitcnt lgkmcnt(3)
	v_lshlrev_b32_e32 v140, 16, v118
	s_waitcnt lgkmcnt(2)
	v_lshlrev_b32_e32 v94, 16, v82
	s_waitcnt lgkmcnt(1)
	v_lshlrev_b32_e32 v141, 16, v119
	v_rcp_f32_e32 v75, v69
	v_div_scale_f32 v69, s[0:1], v68, v68, 1.0
	v_rcp_f32_e32 v70, v69
	s_nop 0
	v_fma_f32 v71, -v69, v70, 1.0
	v_fmac_f32_e32 v70, v71, v70
	v_div_scale_f32 v71, vcc, 1.0, v68, 1.0
	v_mul_f32_e32 v74, v71, v70
	v_fma_f32 v77, -v69, v74, v71
	v_fmac_f32_e32 v74, v77, v70
	v_fma_f32 v69, -v69, v74, v71
	v_div_fmas_f32 v69, v69, v70, v74
	v_div_fixup_f32 v74, v69, v68, 1.0
	v_pk_add_f32 v[68:69], v[74:75], -1.0 op_sel_hi:[1,0]
	v_pk_fma_f32 v[76:77], v[76:77], v[68:69], 1.0 op_sel_hi:[0,1,0]
	v_mfma_f32_16x16x32_bf16 v[68:71], v[64:67], v[32:35], 0
	s_waitcnt vmcnt(2)
	s_nop 6
	v_add_f32_e32 v68, v81, v68
	v_add_f32_e32 v69, v81, v69
	v_mul_f32_e32 v68, 0xbfb8aa3b, v68
	v_mul_f32_e32 v69, 0xbfb8aa3b, v69
	v_exp_f32_e32 v68, v68
	v_exp_f32_e32 v69, v69
	s_nop 0
	v_pk_add_f32 v[68:69], v[68:69], 1.0 op_sel_hi:[1,0]
	v_rcp_f32_e32 v91, v69
	v_rcp_f32_e32 v90, v68
	s_nop 0
	v_pk_add_f32 v[68:69], v[90:91], -1.0 op_sel_hi:[1,0]
	s_waitcnt vmcnt(0)
	v_pk_fma_f32 v[96:97], v[80:81], v[68:69], 1.0 op_sel_hi:[0,1,0]
	v_add_f32_e32 v68, v81, v70
	v_add_f32_e32 v69, v81, v71
	v_mul_f32_e32 v68, 0xbfb8aa3b, v68
	v_mul_f32_e32 v69, 0xbfb8aa3b, v69
	v_exp_f32_e32 v68, v68
	v_exp_f32_e32 v69, v69
	s_nop 0
	v_pk_add_f32 v[68:69], v[68:69], 1.0 op_sel_hi:[1,0]
	v_rcp_f32_e32 v107, v69
	v_div_scale_f32 v69, s[0:1], v68, v68, 1.0
	v_rcp_f32_e32 v70, v69
	s_nop 0
	v_fma_f32 v71, -v69, v70, 1.0
	v_fmac_f32_e32 v70, v71, v70
	v_div_scale_f32 v71, vcc, 1.0, v68, 1.0
	v_mul_f32_e32 v81, v71, v70
	v_fma_f32 v82, -v69, v81, v71
	v_fmac_f32_e32 v81, v82, v70
	global_load_dword v83, v159, s[62:63] offset:128
	global_load_dword v98, v159, s[52:53] offset:128
	global_load_dword v82, v159, s[54:55] offset:128
	v_fma_f32 v69, -v69, v81, v71
	v_div_fmas_f32 v69, v69, v70, v81
	v_div_fixup_f32 v106, v69, v68, 1.0
	v_pk_add_f32 v[68:69], v[106:107], -1.0 op_sel_hi:[1,0]
	ds_read2_b32 v[100:101], v100 offset0:224 offset1:240
	ds_read2_b32 v[104:105], v102 offset0:96 offset1:112
	ds_read2_b32 v[102:103], v103 offset0:224 offset1:240
	ds_read_u16 v145, v117 offset:192
	ds_read_u16 v164, v117 offset:960
	ds_read_u16 v121, v117 offset:1728
	v_pk_fma_f32 v[80:81], v[80:81], v[68:69], 1.0 op_sel_hi:[0,1,0]
	v_mfma_f32_16x16x32_bf16 v[68:71], v[64:67], v[48:51], 0
	ds_read_u16 v108, v117 offset:2496
	ds_read_u16 v133, v117 offset:3264
	ds_read_u16 v134, v117 offset:4032
	v_mfma_f32_16x16x32_bf16 v[64:67], v[64:67], v[56:59], 0
	s_waitcnt lgkmcnt(6)
	v_mov_b32_e32 v144, v103
	s_waitcnt lgkmcnt(2)
	v_lshlrev_b32_e32 v108, 16, v108
	s_waitcnt lgkmcnt(1)
	v_lshlrev_b32_e32 v133, 16, v133
	s_waitcnt lgkmcnt(0)
	v_lshlrev_b32_e32 v135, 16, v134
	v_mov_b32_e32 v134, v133
	s_waitcnt vmcnt(2)
	v_add_f32_e32 v68, v83, v68
	v_add_f32_e32 v69, v83, v69
	v_mul_f32_e32 v68, 0xbfb8aa3b, v68
	v_mul_f32_e32 v69, 0xbfb8aa3b, v69
	v_exp_f32_e32 v68, v68
	v_exp_f32_e32 v69, v69
	v_add_f32_e32 v70, v83, v70
	v_add_f32_e32 v71, v83, v71
	v_mul_f32_e32 v70, 0xbfb8aa3b, v70
	v_pk_add_f32 v[68:69], v[68:69], 1.0 op_sel_hi:[1,0]
	v_mul_f32_e32 v71, 0xbfb8aa3b, v71
	v_exp_f32_e32 v70, v70
	v_exp_f32_e32 v71, v71
	v_rcp_f32_e32 v69, v69
	v_pk_add_f32 v[70:71], v[70:71], 1.0 op_sel_hi:[1,0]
	v_rcp_f32_e32 v68, v68
	s_nop 0
	v_pk_add_f32 v[110:111], v[68:69], -1.0 op_sel_hi:[1,0]
	s_waitcnt vmcnt(0)
	v_pk_fma_f32 v[110:111], v[82:83], v[110:111], 1.0 op_sel_hi:[0,1,0]
	v_rcp_f32_e32 v71, v71
	v_div_scale_f32 v83, s[0:1], v70, v70, 1.0
	v_rcp_f32_e32 v112, v83
	s_nop 0
	v_fma_f32 v114, -v83, v112, 1.0
	v_fmac_f32_e32 v112, v114, v112
	v_div_scale_f32 v114, vcc, 1.0, v70, 1.0
	v_mul_f32_e32 v116, v114, v112
	v_fma_f32 v122, -v83, v116, v114
	v_fmac_f32_e32 v116, v122, v112
	v_fma_f32 v83, -v83, v116, v114
	v_div_fmas_f32 v83, v83, v112, v116
	global_load_dword v128, v159, s[62:63] offset:192
	global_load_dword v112, v159, s[52:53] offset:192
	global_load_dword v116, v159, s[54:55] offset:192
	v_div_fixup_f32 v70, v83, v70, 1.0
	v_pk_add_f32 v[122:123], v[70:71], -1.0 op_sel_hi:[1,0]
	ds_read_u16 v159, v117 offset:224
	ds_read_u16 v165, v117 offset:992
	ds_read_u16 v130, v117 offset:1760
	v_pk_fma_f32 v[82:83], v[82:83], v[122:123], 1.0 op_sel_hi:[0,1,0]
	ds_read_u16 v114, v117 offset:2528
	ds_read_u16 v132, v117 offset:3296
	s_waitcnt lgkmcnt(1)
	v_lshlrev_b32_e32 v114, 16, v114
	s_waitcnt vmcnt(2)
	v_add_f32_e32 v64, v128, v64
	v_add_f32_e32 v65, v128, v65
	v_mul_f32_e32 v64, 0xbfb8aa3b, v64
	v_mul_f32_e32 v65, 0xbfb8aa3b, v65
	v_exp_f32_e32 v64, v64
	v_exp_f32_e32 v65, v65
	s_nop 0
	v_pk_add_f32 v[64:65], v[64:65], 1.0 op_sel_hi:[1,0]
	v_rcp_f32_e32 v127, v65
	v_rcp_f32_e32 v126, v64
	s_nop 0
	v_pk_add_f32 v[64:65], v[126:127], -1.0 op_sel_hi:[1,0]
	s_waitcnt vmcnt(0)
	v_pk_fma_f32 v[122:123], v[116:117], v[64:65], 1.0 op_sel_hi:[0,1,0]
	v_add_f32_e32 v64, v128, v66
	v_add_f32_e32 v65, v128, v67
	v_mul_f32_e32 v64, 0xbfb8aa3b, v64
	v_mul_f32_e32 v65, 0xbfb8aa3b, v65
	v_exp_f32_e32 v64, v64
	v_exp_f32_e32 v65, v65
	ds_read_u16 v117, v117 offset:4064
	v_pk_add_f32 v[64:65], v[64:65], 1.0 op_sel_hi:[1,0]
	v_rcp_f32_e32 v129, v65
	v_and_b32_e32 v67, 64, v179
	v_xor_b32_e32 v66, 1, v179
	v_add_u32_e32 v67, 64, v67
	v_cmp_lt_i32_e32 vcc, v66, v67
	v_rcp_f32_e32 v128, v64
	s_nop 0
	v_pk_add_f32 v[64:65], v[128:129], -1.0 op_sel_hi:[1,0]
	v_cndmask_b32_e32 v66, v179, v66, vcc
	v_lshlrev_b32_e32 v169, 2, v66
	v_xor_b32_e32 v66, 2, v179
	v_cmp_lt_i32_e32 vcc, v66, v67
	s_waitcnt lgkmcnt(0)
	v_pk_fma_f32 v[64:65], v[116:117], v[64:65], 1.0 op_sel_hi:[0,1,0]
	v_lshlrev_b32_e32 v116, 16, v130
	v_cndmask_b32_e32 v66, v179, v66, vcc
	v_lshlrev_b32_e32 v170, 2, v66
	v_xor_b32_e32 v66, 4, v179
	v_cmp_lt_i32_e32 vcc, v66, v67
	v_lshlrev_b32_e32 v131, 16, v117
	v_lshlrev_b32_e32 v117, 16, v132
	v_cndmask_b32_e32 v66, v179, v66, vcc
	v_lshlrev_b32_e32 v171, 2, v66
	v_xor_b32_e32 v66, 8, v179
	v_cmp_lt_i32_e32 vcc, v66, v67
	v_mov_b32_e32 v67, v105
	v_mov_b32_e32 v130, v117
	v_cndmask_b32_e32 v66, v179, v66, vcc
	v_lshlrev_b32_e32 v172, 2, v66
	v_mov_b32_e32 v66, v101
	v_pk_mul_f32 v[136:137], v[66:67], v[114:115] op_sel:[1,0] op_sel_hi:[0,0]
	v_pk_fma_f32 v[66:67], v[66:67], v[116:117], v[136:137]
	v_lshlrev_b32_e32 v132, 16, v121
	v_pk_fma_f32 v[66:67], v[144:145], v[130:131], v[66:67] op_sel_hi:[0,1,1]
	v_pk_mul_f32 v[64:65], v[64:65], v[66:67]
	v_pk_mul_f32 v[130:131], v[112:113], v[66:67] op_sel_hi:[0,1]
	v_mov_b32_e32 v66, v100
	v_mov_b32_e32 v67, v104
	v_pk_mul_f32 v[136:137], v[66:67], v[108:109] op_sel:[1,0] op_sel_hi:[0,0]
	v_pk_fma_f32 v[66:67], v[66:67], v[132:133], v[136:137]
	v_lshlrev_b32_e32 v121, 16, v120
	v_pk_fma_f32 v[134:135], v[102:103], v[134:135], v[66:67] op_sel_hi:[0,1,1]
	v_pk_mul_f32 v[66:67], v[82:83], v[134:135]
	v_mov_b32_e32 v82, v73
	v_mov_b32_e32 v83, v79
	v_pk_mul_f32 v[118:119], v[82:83], v[94:95] op_sel:[1,0] op_sel_hi:[0,0]
	v_mov_b32_e32 v120, v141
	v_pk_fma_f32 v[82:83], v[82:83], v[140:141], v[118:119]
	v_pk_mul_f32 v[166:167], v[98:99], v[134:135] op_sel_hi:[0,1]
	v_pk_fma_f32 v[82:83], v[168:169], v[120:121], v[82:83] op_sel_hi:[0,1,1]
	v_pk_mul_f32 v[120:121], v[92:93], v[82:83] op_sel_hi:[0,1]
	v_pk_mul_f32 v[118:119], v[80:81], v[82:83]
	v_mov_b32_e32 v82, v72
	v_mov_b32_e32 v83, v78
	v_pk_mul_f32 v[136:137], v[82:83], v[86:87] op_sel:[1,0] op_sel_hi:[0,0]
	v_lshlrev_b32_e32 v135, 16, v99
	v_mov_b32_e32 v134, v143
	v_pk_fma_f32 v[82:83], v[82:83], v[142:143], v[136:137]
	v_pk_mul_f32 v[80:81], v[120:121], v[120:121]
	v_pk_fma_f32 v[82:83], v[84:85], v[134:135], v[82:83] op_sel_hi:[0,1,1]
	v_pk_mul_f32 v[138:139], v[0:1], v[82:83] op_sel_hi:[0,1]
	v_pk_mul_f32 v[136:137], v[76:77], v[82:83]
	v_pk_fma_f32 v[76:77], v[138:139], v[138:139], v[80:81]
	v_mov_b32_e32 v117, v114
	v_pk_fma_f32 v[76:77], v[166:167], v[166:167], v[76:77]
	v_mov_b32_e32 v114, v105
	v_pk_fma_f32 v[76:77], v[130:131], v[130:131], v[76:77]
	s_nop 1
	v_mov_b32_dpp v80, v76 quad_perm:[1,0,3,2] row_mask:0xf bank_mask:0xf
	s_nop 1
	v_mov_b32_dpp v81, v77 quad_perm:[1,0,3,2] row_mask:0xf bank_mask:0xf
	v_mov_b32_e32 v133, v108
	v_mov_b32_e32 v141, v94
	v_mov_b32_e32 v94, v73
	v_mov_b32_e32 v143, v86
	s_waitcnt lgkmcnt(0)
	v_pk_add_f32 v[76:77], v[76:77], v[80:81]
	s_nop 1
	v_mov_b32_dpp v80, v76 quad_perm:[2,3,0,1] row_mask:0xf bank_mask:0xf
	s_nop 1
	v_mov_b32_dpp v81, v77 quad_perm:[2,3,0,1] row_mask:0xf bank_mask:0xf
	s_waitcnt lgkmcnt(0)
	v_pk_add_f32 v[76:77], v[76:77], v[80:81]
	s_nop 1
	v_mov_b32_dpp v80, v76 row_shl:4 row_mask:0xf bank_mask:0x5
	s_nop 1
	v_mov_b32_dpp v80, v76 row_shr:4 row_mask:0xf bank_mask:0xa
	s_nop 1
	v_mov_b32_dpp v81, v77 row_shl:4 row_mask:0xf bank_mask:0x5
	s_nop 1
	v_mov_b32_dpp v81, v77 row_shr:4 row_mask:0xf bank_mask:0xa
	s_waitcnt lgkmcnt(0)
	v_pk_add_f32 v[76:77], v[76:77], v[80:81]
	s_nop 1
	v_mov_b32_dpp v80, v76 row_shl:8 row_mask:0xf bank_mask:0x3
	s_nop 1
	v_mov_b32_dpp v80, v76 row_shr:8 row_mask:0xf bank_mask:0xc
	s_nop 1
	v_mov_b32_dpp v81, v77 row_shl:8 row_mask:0xf bank_mask:0x3
	s_nop 1
	v_mov_b32_dpp v81, v77 row_shr:8 row_mask:0xf bank_mask:0xc
	s_waitcnt lgkmcnt(0)
	v_pk_add_f32 v[76:77], v[76:77], v[80:81]
	s_nop 0
	v_pk_add_f32 v[76:77], v[76:77], s[4:5] op_sel_hi:[1,0]
	s_nop 0
	v_mul_f32_e32 v80, 0x4b800000, v76
	v_cmp_gt_f32_e64 s[0:1], s29, v76
	v_cmp_gt_f32_e32 vcc, s29, v77
	s_nop 0
	v_cndmask_b32_e64 v76, v76, v80, s[0:1]
	v_mul_f32_e32 v80, 0x4b800000, v77
	v_cndmask_b32_e32 v77, v77, v80, vcc
	v_rsq_f32_e32 v76, v76
	v_rsq_f32_e32 v77, v77
	s_nop 0
	v_pk_mul_f32 v[80:81], v[76:77], s[10:11] op_sel_hi:[1,0]
	s_nop 0
	v_cndmask_b32_e32 v135, v77, v81, vcc
	v_cndmask_b32_e64 v134, v76, v80, s[0:1]
	v_pk_mul_f32 v[80:81], v[138:139], v[134:135]
	v_pk_mul_f32 v[76:77], v[166:167], v[134:135]
	v_pk_mul_f32 v[138:139], v[74:75], v[80:81]
	v_pk_mul_f32 v[74:75], v[70:71], v[76:77]
	v_lshlrev_b32_e32 v71, 16, v165
	v_lshlrev_b32_e32 v70, 16, v159
	v_pk_mul_f32 v[82:83], v[120:121], v[134:135]
	v_pk_mov_b32 v[166:167], v[70:71], v[116:117] op_sel:[1,0]
	v_pk_mul_f32 v[120:121], v[106:107], v[82:83]
	v_mov_b32_e32 v106, v101
	v_pk_mul_f32 v[166:167], v[114:115], v[166:167] op_sel_hi:[0,1]
	v_pk_fma_f32 v[70:71], v[106:107], v[70:71], v[166:167] op_sel_hi:[0,1,1]
	v_pk_fma_f32 v[106:107], v[144:145], v[116:117], v[70:71] op_sel_hi:[0,1,1]
	v_lshlrev_b32_e32 v117, 16, v164
	v_lshlrev_b32_e32 v116, 16, v145
	v_pk_mul_f32 v[70:71], v[122:123], v[106:107]
	v_pk_mov_b32 v[122:123], v[116:117], v[132:133] op_sel:[1,0]
	v_pk_mul_f32 v[106:107], v[112:113], v[106:107] op_sel_hi:[0,1]
	v_pk_mul_f32 v[104:105], v[104:105], v[122:123] op_sel_hi:[0,1]
	v_pk_fma_f32 v[100:101], v[100:101], v[116:117], v[104:105] op_sel_hi:[0,1,1]
	v_pk_fma_f32 v[100:101], v[102:103], v[132:133], v[100:101] op_sel_hi:[0,1,1]
	v_pk_mul_f32 v[116:117], v[110:111], v[100:101]
	v_pk_mul_f32 v[98:99], v[98:99], v[100:101] op_sel_hi:[0,1]
	v_lshlrev_b32_e32 v101, 16, v115
	v_lshlrev_b32_e32 v100, 16, v113
	v_mov_b32_e32 v102, v79
	v_pk_mov_b32 v[104:105], v[100:101], v[140:141] op_sel:[1,0]
	s_nop 0
	v_pk_mul_f32 v[102:103], v[102:103], v[104:105] op_sel_hi:[0,1]
	v_pk_fma_f32 v[94:95], v[94:95], v[100:101], v[102:103] op_sel_hi:[0,1,1]
	v_pk_fma_f32 v[94:95], v[168:169], v[140:141], v[94:95] op_sel_hi:[0,1,1]
	v_pk_mul_f32 v[132:133], v[96:97], v[94:95]
	v_lshlrev_b32_e32 v97, 16, v87
	v_lshlrev_b32_e32 v96, 16, v109
	v_pk_mov_b32 v[86:87], v[96:97], v[142:143] op_sel:[1,0]
	v_pk_mul_f32 v[92:93], v[92:93], v[94:95] op_sel_hi:[0,1]
	v_pk_mul_f32 v[78:79], v[78:79], v[86:87] op_sel_hi:[0,1]
	v_pk_fma_f32 v[72:73], v[72:73], v[96:97], v[78:79] op_sel_hi:[0,1,1]
	v_pk_fma_f32 v[72:73], v[84:85], v[142:143], v[72:73] op_sel_hi:[0,1,1]
	v_pk_mul_f32 v[94:95], v[92:93], v[92:93]
	v_pk_mul_f32 v[78:79], v[0:1], v[72:73] op_sel_hi:[0,1]
	v_pk_mul_f32 v[142:143], v[88:89], v[72:73]
	v_pk_fma_f32 v[72:73], v[78:79], v[78:79], v[94:95]
	s_nop 0
	v_pk_fma_f32 v[72:73], v[98:99], v[98:99], v[72:73]
	s_nop 0
	v_pk_fma_f32 v[72:73], v[106:107], v[106:107], v[72:73]
	s_nop 1
	v_mov_b32_dpp v84, v72 quad_perm:[1,0,3,2] row_mask:0xf bank_mask:0xf
	s_nop 1
	v_mov_b32_dpp v85, v73 quad_perm:[1,0,3,2] row_mask:0xf bank_mask:0xf
	s_waitcnt lgkmcnt(0)
	v_pk_add_f32 v[72:73], v[72:73], v[84:85]
	s_nop 1
	v_mov_b32_dpp v84, v72 quad_perm:[2,3,0,1] row_mask:0xf bank_mask:0xf
	s_nop 1
	v_mov_b32_dpp v85, v73 quad_perm:[2,3,0,1] row_mask:0xf bank_mask:0xf
	s_waitcnt lgkmcnt(0)
	v_pk_add_f32 v[72:73], v[72:73], v[84:85]
	s_nop 1
	v_mov_b32_dpp v84, v72 row_shl:4 row_mask:0xf bank_mask:0x5
	s_nop 1
	v_mov_b32_dpp v84, v72 row_shr:4 row_mask:0xf bank_mask:0xa
	s_nop 1
	v_mov_b32_dpp v85, v73 row_shl:4 row_mask:0xf bank_mask:0x5
	s_nop 1
	v_mov_b32_dpp v85, v73 row_shr:4 row_mask:0xf bank_mask:0xa
	s_waitcnt lgkmcnt(0)
	v_pk_add_f32 v[72:73], v[72:73], v[84:85]
	s_nop 1
	v_mov_b32_dpp v84, v72 row_shl:8 row_mask:0xf bank_mask:0x3
	s_nop 1
	v_mov_b32_dpp v84, v72 row_shr:8 row_mask:0xf bank_mask:0xc
	s_nop 1
	v_mov_b32_dpp v85, v73 row_shl:8 row_mask:0xf bank_mask:0x3
	s_nop 1
	v_mov_b32_dpp v85, v73 row_shr:8 row_mask:0xf bank_mask:0xc
	s_waitcnt lgkmcnt(0)
	v_pk_add_f32 v[72:73], v[72:73], v[84:85]
	s_nop 0
	v_pk_add_f32 v[72:73], v[72:73], s[4:5] op_sel_hi:[1,0]
	s_nop 0
	v_mul_f32_e32 v0, 0x4b800000, v72
	v_cmp_gt_f32_e64 s[0:1], s29, v72
	v_cmp_gt_f32_e32 vcc, s29, v73
	s_nop 0
	v_cndmask_b32_e64 v0, v72, v0, s[0:1]
	v_rsq_f32_e32 v72, v0
	v_mul_f32_e32 v0, 0x4b800000, v73
	v_cndmask_b32_e32 v0, v73, v0, vcc
	v_rsq_f32_e32 v73, v0
	s_nop 0
	v_pk_mul_f32 v[84:85], v[72:73], s[10:11] op_sel_hi:[1,0]
	s_nop 0
	v_cndmask_b32_e32 v73, v73, v85, vcc
	v_cndmask_b32_e64 v72, v72, v84, s[0:1]
	v_pk_mul_f32 v[84:85], v[78:79], v[72:73]
	v_pk_mul_f32 v[78:79], v[98:99], v[72:73]
	v_pk_mul_f32 v[86:87], v[92:93], v[72:73]
	v_pk_mul_f32 v[122:123], v[68:69], v[78:79]
	v_pk_mul_f32 v[112:113], v[106:107], v[72:73]
	v_pk_mul_f32 v[68:69], v[130:131], v[134:135]
	v_pk_mul_f32 v[144:145], v[2:3], v[84:85]
	v_pk_mul_f32 v[140:141], v[90:91], v[86:87]
	v_pk_mul_f32 v[114:115], v[126:127], v[112:113]
	v_pk_mul_f32 v[72:73], v[128:129], v[68:69]

.LBB0_850:
	s_or_b64 exec, exec, s[0:1]
	s_movk_i32 s0, 0x100
	v_ashrrev_i32_e32 v202, 6, v196
	v_cmp_gt_u32_e64 s[36:37], s0, v196
	s_movk_i32 s0, 0xff
	v_and_b32_e32 v198, 3, v202
	s_waitcnt lgkmcnt(0)
	s_barrier
	v_cmp_lt_u32_e64 s[38:39], s0, v196
	s_lshl_b32 s0, s74, 6
	v_lshlrev_b32_e32 v195, 4, v198
	v_or_b32_e32 v191, s0, v192
	v_and_b32_e32 v200, 48, v196
	v_lshlrev_b32_e32 v118, 1, v192
	v_or_b32_e32 v197, v195, v192
	v_lshlrev_b32_e32 v190, 2, v191
	v_lshl_add_u32 v116, v192, 2, 0
	v_add_lshl_u32 v201, v192, s0, 2
	s_and_saveexec_b64 s[0:1], s[38:39]
	s_xor_b64 s[44:45], exec, s[0:1]
	s_cbranch_execz .LBB0_852
	v_readlane_b32 s80, v252, 18
	v_readlane_b32 s94, v252, 32
	v_readlane_b32 s95, v252, 33
	v_mul_u32_u24_e32 v0, 0x190, v197
	v_readlane_b32 s0, v254, 52
	v_readlane_b32 s81, v252, 19
	v_readlane_b32 s82, v252, 20
	v_add3_u32 v0, s0, v0, v200
	global_load_dword v76, v190, s[94:95]
	ds_read_b128 v[64:67], v0 offset:128
	v_readlane_b32 s83, v252, 21
	v_readlane_b32 s84, v252, 22
	v_readlane_b32 s85, v252, 23
	v_readlane_b32 s86, v252, 24
	v_readlane_b32 s87, v252, 25
	v_readlane_b32 s88, v252, 26
	v_readlane_b32 s89, v252, 27
	v_readlane_b32 s90, v252, 28
	v_readlane_b32 s91, v252, 29
	v_readlane_b32 s92, v252, 30
	v_readlane_b32 s93, v252, 31
	v_lshl_or_b32 v0, v194, 2, v195
	s_mov_b64 s[54:55], s[94:95]
	v_readlane_b32 s80, v252, 35
	v_mul_u32_u24_e32 v2, 0x300, v0
	v_readlane_b32 s81, v252, 36
	v_readlane_b32 s82, v252, 37
	v_readlane_b32 s83, v252, 38
	v_readlane_b32 s84, v252, 39
	v_readlane_b32 s85, v252, 40
	v_readlane_b32 s86, v252, 41
	v_readlane_b32 s87, v252, 42
	v_readlane_b32 s88, v252, 43
	v_readlane_b32 s89, v252, 44
	v_readlane_b32 s90, v252, 45
	v_readlane_b32 s91, v252, 46
	v_readlane_b32 s92, v252, 47
	v_readlane_b32 s93, v252, 48
	s_mov_b64 s[80:81], s[84:85]
	v_add_u32_e32 v77, 0xc400, v116
	v_add_u32_e32 v90, 0xcc00, v116
	v_add_u32_e32 v96, 0xd000, v116
	v_add3_u32 v85, 0, v2, v118
	s_waitcnt lgkmcnt(0)
	v_mfma_f32_16x16x32_bf16 v[72:75], v[64:67], v[24:27], 0
	s_mov_b64 s[82:83], s[86:87]
	global_load_dword v3, v190, s[80:81]
	global_load_dword v0, v190, s[82:83]
	ds_read2_b32 v[68:69], v77 offset0:192 offset1:208
	ds_read2_b32 v[80:81], v90 offset0:64 offset1:80
	ds_read2_b32 v[70:71], v96 offset0:192 offset1:208
	ds_read_u16 v2, v85 offset:128
	ds_read_u16 v82, v85 offset:160
	ds_read_u16 v79, v85 offset:896
	ds_read_u16 v107, v85 offset:1664
	ds_read_u16 v88, v85 offset:2432
	v_mfma_f32_16x16x32_bf16 v[112:115], v[64:67], v[48:51], 0
	s_waitcnt lgkmcnt(4)
	v_lshlrev_b32_e32 v78, 16, v2
	v_mov_b32_e32 v137, v81
	v_mov_b32_e32 v149, v71
	v_mov_b32_e32 v150, v81
	v_mov_b32_e32 v151, v80
	v_mov_b32_e32 v152, v71
	v_mov_b32_e32 v153, v70
	s_mov_b32 s4, 0x2b8cbccc
	v_readlane_b32 s94, v252, 49
	v_readlane_b32 s95, v252, 50
	s_mov_b64 s[84:85], s[88:89]
	s_mov_b64 s[86:87], s[90:91]
	s_mov_b64 s[88:89], s[92:93]
	s_waitcnt vmcnt(2)
	v_add_f32_e32 v2, v76, v72
	v_mul_f32_e32 v2, 0xbfb8aa3b, v2
	v_exp_f32_e32 v84, v2
	v_add_f32_e32 v2, v76, v73
	v_mul_f32_e32 v2, 0xbfb8aa3b, v2
	v_exp_f32_e32 v86, v2
	ds_read_u16 v2, v85 offset:3200
	s_waitcnt lgkmcnt(0)
	v_lshlrev_b32_e32 v83, 16, v2
	v_add_f32_e32 v2, v76, v74
	v_mul_f32_e32 v2, 0xbfb8aa3b, v2
	v_exp_f32_e32 v87, v2
	ds_read_u16 v2, v85 offset:3968
	v_pk_add_f32 v[86:87], v[86:87], 1.0 op_sel_hi:[1,0]
	s_waitcnt lgkmcnt(0)
	v_lshlrev_b32_e32 v89, 16, v2
	v_add_f32_e32 v2, v76, v75
	v_mul_f32_e32 v2, 0xbfb8aa3b, v2
	v_exp_f32_e32 v93, v2
	global_load_dword v2, v201, s[54:55] offset:64
	global_load_dword v101, v201, s[80:81] offset:64
	global_load_dword v102, v201, s[82:83] offset:64
	v_mfma_f32_16x16x32_bf16 v[72:75], v[64:67], v[32:35], 0
	ds_read_u16 v134, v85 offset:928
	ds_read_u16 v135, v85 offset:1696
	v_mfma_f32_16x16x32_bf16 v[64:67], v[64:67], v[56:59], 0
	s_waitcnt vmcnt(2)
	s_nop 3
	v_add_f32_e32 v72, v2, v72
	v_add_f32_e32 v73, v2, v73
	v_mul_f32_e32 v72, 0xbfb8aa3b, v72
	v_mul_f32_e32 v73, 0xbfb8aa3b, v73
	v_exp_f32_e32 v92, v72
	ds_read_u16 v72, v85 offset:2464
	v_exp_f32_e32 v108, v73
	ds_read_u16 v73, v85 offset:3232
	v_pk_add_f32 v[92:93], v[92:93], 1.0 op_sel_hi:[1,0]
	s_waitcnt lgkmcnt(0)
	v_lshlrev_b32_e32 v105, 16, v73
	v_add_f32_e32 v73, v2, v74
	v_add_f32_e32 v2, v2, v75
	v_mul_f32_e32 v73, 0xbfb8aa3b, v73
	v_mul_f32_e32 v2, 0xbfb8aa3b, v2
	v_exp_f32_e32 v109, v73
	ds_read_u16 v73, v85 offset:4000
	v_exp_f32_e32 v75, v2
	global_load_dword v76, v201, s[54:55] offset:128
	global_load_dword v91, v201, s[80:81] offset:128
	global_load_dword v2, v201, s[82:83] offset:128
	ds_read2_b32 v[94:95], v77 offset0:224 offset1:240
	ds_read2_b32 v[98:99], v90 offset0:96 offset1:112
	ds_read2_b32 v[96:97], v96 offset0:224 offset1:240
	ds_read_u16 v104, v85 offset:192
	ds_read_u16 v100, v85 offset:960
	ds_read_u16 v130, v85 offset:1728
	s_waitcnt lgkmcnt(4)
	v_mov_b32_e32 v128, v99
	v_mov_b32_e32 v129, v98
	v_mov_b32_e32 v116, v95
	v_mov_b32_e32 v117, v99
	s_waitcnt lgkmcnt(3)
	v_mov_b32_e32 v132, v97
	v_mov_b32_e32 v133, v96
	s_waitcnt lgkmcnt(1)
	v_lshlrev_b32_e32 v144, 16, v100
	s_waitcnt lgkmcnt(0)
	v_lshlrev_b32_e32 v145, 16, v130
	v_mov_b32_e32 v130, v94
	v_lshlrev_b32_e32 v73, 16, v73
	v_mov_b32_e32 v148, v96
	v_pk_add_f32 v[108:109], v[108:109], 1.0 op_sel_hi:[1,0]
	s_waitcnt vmcnt(2)
	v_add_f32_e32 v77, v76, v113
	v_mul_f32_e32 v77, 0xbfb8aa3b, v77
	v_add_f32_e32 v74, v76, v112
	ds_read_u16 v112, v85 offset:2496
	v_exp_f32_e32 v120, v77
	ds_read_u16 v77, v85 offset:3264
	v_mul_f32_e32 v74, 0xbfb8aa3b, v74
	v_exp_f32_e32 v74, v74
	s_waitcnt lgkmcnt(0)
	v_lshlrev_b32_e32 v119, 16, v77
	v_add_f32_e32 v77, v76, v114
	ds_read_u16 v114, v85 offset:4032
	global_load_dword v110, v201, s[54:55] offset:192
	global_load_dword v90, v201, s[80:81] offset:192
	global_load_dword v106, v201, s[82:83] offset:192
	v_add_f32_e32 v76, v76, v115
	v_mul_f32_e32 v77, 0xbfb8aa3b, v77
	v_mul_f32_e32 v76, 0xbfb8aa3b, v76
	v_exp_f32_e32 v121, v77
	v_exp_f32_e32 v77, v76
	ds_read_u16 v113, v85 offset:224
	ds_read_u16 v111, v85 offset:992
	ds_read_u16 v115, v85 offset:1760
	ds_read_u16 v118, v85 offset:2528
	ds_read_u16 v126, v85 offset:3296
	v_pk_add_f32 v[74:75], v[74:75], 1.0 op_sel_hi:[1,0]
	s_waitcnt lgkmcnt(3)
	v_lshlrev_b32_e32 v122, 16, v111
	s_waitcnt vmcnt(2)
	v_add_f32_e32 v64, v110, v64
	v_mul_f32_e32 v64, 0xbfb8aa3b, v64
	v_exp_f32_e32 v76, v64
	v_add_f32_e32 v64, v110, v65
	v_add_f32_e32 v65, v110, v66
	ds_read_u16 v66, v85 offset:4064
	v_mul_f32_e32 v64, 0xbfb8aa3b, v64
	v_mul_f32_e32 v65, 0xbfb8aa3b, v65
	v_exp_f32_e32 v64, v64
	v_exp_f32_e32 v65, v65
	s_waitcnt lgkmcnt(0)
	v_lshlrev_b32_e32 v103, 16, v66
	v_add_f32_e32 v66, v110, v67
	v_mul_f32_e32 v66, 0xbfb8aa3b, v66
	v_and_b32_e32 v67, 64, v179
	v_exp_f32_e32 v85, v66
	v_xor_b32_e32 v66, 1, v179
	v_add_u32_e32 v67, 64, v67
	v_cmp_lt_i32_e32 vcc, v66, v67
	v_pk_add_f32 v[64:65], v[64:65], 1.0 op_sel_hi:[1,0]
	v_lshlrev_b32_e32 v123, 16, v118
	v_cndmask_b32_e32 v66, v179, v66, vcc
	v_lshlrev_b32_e32 v143, 2, v66
	v_xor_b32_e32 v66, 2, v179
	v_cmp_lt_i32_e32 vcc, v66, v67
	v_pk_add_f32 v[76:77], v[76:77], 1.0 op_sel_hi:[1,0]
	v_lshlrev_b32_e32 v127, 16, v126
	v_cndmask_b32_e32 v66, v179, v66, vcc
	v_lshlrev_b32_e32 v142, 2, v66
	v_xor_b32_e32 v66, 4, v179
	v_cmp_lt_i32_e32 vcc, v66, v67
	v_mov_b32_e32 v126, v123
	v_pk_add_f32 v[84:85], v[84:85], 1.0 op_sel_hi:[1,0]
	v_cndmask_b32_e32 v66, v179, v66, vcc
	v_lshlrev_b32_e32 v141, 2, v66
	v_xor_b32_e32 v66, 8, v179
	v_cmp_lt_i32_e32 vcc, v66, v67
	s_nop 1
	v_cndmask_b32_e32 v66, v179, v66, vcc
	v_lshlrev_b32_e32 v140, 2, v66
	v_rcp_f32_e32 v111, v65
	v_lshlrev_b32_e32 v67, 16, v112
	v_lshlrev_b32_e32 v66, 16, v113
	v_rcp_f32_e32 v110, v64
	v_mov_b32_e32 v64, v95
	v_mov_b32_e32 v65, v94
	v_rcp_f32_e32 v113, v77
	v_mov_b32_e32 v118, v122
	v_rcp_f32_e32 v112, v76
	v_lshlrev_b32_e32 v77, 16, v114
	v_lshlrev_b32_e32 v76, 16, v115
	v_pk_mul_f32 v[114:115], v[128:129], v[118:119]
	v_mov_b32_e32 v136, v98
	v_pk_fma_f32 v[64:65], v[64:65], v[66:67], v[114:115]
	v_mov_b32_e32 v66, v97
	v_pk_fma_f32 v[138:139], v[132:133], v[76:77], v[64:65]
	v_pk_mul_f32 v[76:77], v[116:117], v[76:77] op_sel:[1,0] op_sel_hi:[0,0]
	v_mov_b32_e32 v64, v112
	v_mov_b32_e32 v65, v110
	v_pk_fma_f32 v[76:77], v[116:117], v[122:123], v[76:77]
	v_pk_add_f32 v[64:65], v[64:65], -1.0 op_sel_hi:[1,0]
	v_pk_fma_f32 v[128:129], v[66:67], v[126:127], v[76:77] op_sel_hi:[0,1,1]
	s_waitcnt vmcnt(0)
	v_pk_fma_f32 v[64:65], v[106:107], v[64:65], 1.0 op_sel_hi:[0,1,0]
	v_mov_b32_e32 v76, v138
	v_mov_b32_e32 v77, v128
	v_pk_mul_f32 v[76:77], v[64:65], v[76:77]
	v_pk_add_f32 v[64:65], v[120:121], 1.0 op_sel_hi:[1,0]
	v_pk_mul_f32 v[116:117], v[90:91], v[128:129] op_sel_hi:[0,1]
	v_mov_b32_e32 v131, v69
	v_pk_mul_f32 v[114:115], v[90:91], v[138:139]
	v_rcp_f32_e32 v121, v65
	v_rcp_f32_e32 v120, v64
	v_mov_b32_e32 v64, v121
	v_mov_b32_e32 v65, v113
	v_pk_add_f32 v[64:65], v[64:65], -1.0 op_sel_hi:[1,0]
	v_mov_b32_e32 v66, v145
	v_pk_fma_f32 v[146:147], v[2:3], v[64:65], 1.0 op_sel_hi:[0,1,0]
	v_lshlrev_b32_e32 v65, 16, v72
	v_lshlrev_b32_e32 v64, 16, v104
	v_mov_b32_e32 v118, v67
	v_pk_mul_f32 v[66:67], v[98:99], v[66:67] op_sel_hi:[0,1]
	v_pk_fma_f32 v[66:67], v[94:95], v[144:145], v[66:67] op_sel_hi:[0,1,1]
	v_rcp_f32_e32 v133, v75
	v_pk_fma_f32 v[66:67], v[96:97], v[118:119], v[66:67] op_sel_hi:[0,1,1]
	v_mov_b32_e32 v100, v91
	v_mov_b32_e32 v138, v67
	v_mov_b32_e32 v104, v144
	v_rcp_f32_e32 v132, v74
	v_pk_mul_f32 v[74:75], v[136:137], v[104:105]
	v_mov_b32_e32 v72, v145
	v_pk_fma_f32 v[74:75], v[130:131], v[64:65], v[74:75]
	v_mov_b32_e32 v104, v65
	v_pk_fma_f32 v[148:149], v[148:149], v[72:73], v[74:75]
	v_mov_b32_e32 v72, v132
	v_mov_b32_e32 v73, v120
	v_pk_add_f32 v[72:73], v[72:73], -1.0 op_sel_hi:[1,0]
	v_mov_b32_e32 v74, v148
	v_pk_fma_f32 v[72:73], v[2:3], v[72:73], 1.0 op_sel_hi:[0,1,0]
	v_mov_b32_e32 v2, v91
	v_pk_mul_f32 v[118:119], v[2:3], v[66:67] op_sel_hi:[0,1]
	v_mov_b32_e32 v75, v66
	v_pk_mul_f32 v[72:73], v[72:73], v[74:75]
	v_pk_mul_f32 v[74:75], v[146:147], v[138:139]
	v_rcp_f32_e32 v109, v109
	v_lshlrev_b32_e32 v138, 16, v82
	v_lshlrev_b32_e32 v139, 16, v88
	v_lshlrev_b32_e32 v67, 16, v135
	v_lshlrev_b32_e32 v66, 16, v134
	v_mov_b32_e32 v134, v109
	v_mov_b32_e32 v135, v133
	v_pk_add_f32 v[134:135], v[134:135], -1.0 op_sel_hi:[1,0]
	v_pk_fma_f32 v[144:145], v[102:103], v[134:135], 1.0 op_sel_hi:[0,1,0]
	v_rcp_f32_e32 v135, v93
	v_mov_b32_e32 v146, v69
	v_mov_b32_e32 v147, v68
	v_rcp_f32_e32 v108, v108
	v_rcp_f32_e32 v134, v92
	v_mov_b32_e32 v82, v66
	v_pk_mul_f32 v[92:93], v[150:151], v[82:83]
	v_mov_b32_e32 v88, v67
	v_pk_fma_f32 v[92:93], v[146:147], v[138:139], v[92:93]
	v_mov_b32_e32 v64, v67
	v_mov_b32_e32 v2, v101
	v_pk_fma_f32 v[92:93], v[152:153], v[88:89], v[92:93]
	v_mov_b32_e32 v82, v81
	v_pk_mul_f32 v[88:89], v[2:3], v[92:93]
	v_mov_b32_e32 v2, v69
	v_pk_mul_f32 v[64:65], v[82:83], v[64:65] op_sel_hi:[0,1]
	v_pk_fma_f32 v[64:65], v[2:3], v[66:67], v[64:65] op_sel_hi:[0,1,1]
	v_mov_b32_e32 v2, v71
	v_pk_fma_f32 v[66:67], v[2:3], v[104:105], v[64:65] op_sel_hi:[0,1,1]
	v_mov_b32_e32 v2, v101
	v_pk_mul_f32 v[130:131], v[100:101], v[148:149]
	v_pk_mul_f32 v[100:101], v[2:3], v[66:67] op_sel_hi:[0,1]
	v_mov_b32_e32 v148, v67
	v_mov_b32_e32 v65, v66
	v_pk_mul_f32 v[66:67], v[144:145], v[148:149]
	v_lshlrev_b32_e32 v144, 16, v79
	v_rcp_f32_e32 v87, v87
	v_mov_b32_e32 v146, v134
	v_mov_b32_e32 v147, v108
	v_pk_add_f32 v[146:147], v[146:147], -1.0 op_sel_hi:[1,0]
	v_rcp_f32_e32 v86, v86
	v_mov_b32_e32 v104, v87
	v_mov_b32_e32 v105, v135
	v_pk_fma_f32 v[146:147], v[102:103], v[146:147], 1.0 op_sel_hi:[0,1,0]
	v_mov_b32_e32 v64, v92
	v_pk_add_f32 v[104:105], v[104:105], -1.0 op_sel_hi:[1,0]
	v_pk_mul_f32 v[64:65], v[146:147], v[64:65]
	v_pk_fma_f32 v[146:147], v[0:1], v[104:105], 1.0 op_sel_hi:[0,1,0]
	v_rcp_f32_e32 v105, v85
	v_mov_b32_e32 v85, v86
	v_lshlrev_b32_e32 v145, 16, v107
	v_mov_b32_e32 v122, v144
	v_rcp_f32_e32 v104, v84
	s_nop 0
	v_mov_b32_e32 v84, v104
	v_mov_b32_e32 v69, v99
	v_mov_b32_e32 v79, v127
	v_pk_add_f32 v[84:85], v[84:85], -1.0 op_sel_hi:[1,0]
	v_pk_mul_f32 v[78:79], v[68:69], v[78:79]
	v_mov_b32_e32 v81, v95
	v_pk_fma_f32 v[148:149], v[0:1], v[84:85], 1.0 op_sel_hi:[0,1,0]
	v_mov_b32_e32 v84, v111
	v_mov_b32_e32 v85, v105
	v_mov_b32_e32 v71, v97
	v_pk_fma_f32 v[78:79], v[80:81], v[122:123], v[78:79]
	v_mov_b32_e32 v102, v145
	v_pk_add_f32 v[84:85], v[84:85], -1.0 op_sel_hi:[1,0]
	v_pk_fma_f32 v[94:95], v[70:71], v[102:103], v[78:79]
	v_pk_fma_f32 v[84:85], v[106:107], v[84:85], 1.0 op_sel_hi:[0,1,0]
	v_mov_b32_e32 v78, v129
	v_mov_b32_e32 v79, v95
	v_mov_b32_e32 v138, v145
	v_pk_mul_f32 v[78:79], v[84:85], v[78:79]
	v_mov_b32_e32 v84, v3
	v_mov_b32_e32 v85, v90
	v_pk_mul_f32 v[84:85], v[84:85], v[94:95]
	v_pk_mul_f32 v[80:81], v[80:81], v[138:139] op_sel_hi:[0,1]
	v_pk_fma_f32 v[68:69], v[68:69], v[144:145], v[80:81] op_sel_hi:[0,1,1]
	v_mov_b32_e32 v80, v84
	v_mov_b32_e32 v81, v131
	v_pk_mul_f32 v[80:81], v[80:81], v[80:81]
	v_mov_b32_e32 v136, v130
	v_mov_b32_e32 v137, v115
	v_pk_fma_f32 v[80:81], v[88:89], v[88:89], v[80:81]
	v_mov_b32_e32 v90, v114
	v_mov_b32_e32 v91, v85
	v_pk_fma_f32 v[80:81], v[136:137], v[136:137], v[80:81]
	v_mov_b32_e32 v82, v139
	v_pk_fma_f32 v[80:81], v[90:91], v[90:91], v[80:81]
	s_nop 1
	v_mov_b32_dpp v90, v80 quad_perm:[1,0,3,2] row_mask:0xf bank_mask:0xf
	s_nop 1
	v_mov_b32_dpp v91, v81 quad_perm:[1,0,3,2] row_mask:0xf bank_mask:0xf
	v_pk_fma_f32 v[70:71], v[70:71], v[82:83], v[68:69] op_sel_hi:[0,1,1]
	v_mov_b32_e32 v0, v3
	v_pk_mul_f32 v[2:3], v[0:1], v[70:71] op_sel_hi:[0,1]
	v_pk_mul_f32 v[82:83], v[100:101], v[100:101]
	s_waitcnt lgkmcnt(0)
	v_pk_add_f32 v[80:81], v[80:81], v[90:91]
	s_nop 1
	v_mov_b32_dpp v90, v80 quad_perm:[2,3,0,1] row_mask:0xf bank_mask:0xf
	s_nop 1
	v_mov_b32_dpp v91, v81 quad_perm:[2,3,0,1] row_mask:0xf bank_mask:0xf
	v_pk_fma_f32 v[82:83], v[2:3], v[2:3], v[82:83]
	v_mov_b32_e32 v92, v71
	v_pk_fma_f32 v[82:83], v[118:119], v[118:119], v[82:83]
	v_mov_b32_e32 v95, v70
	s_waitcnt lgkmcnt(0)
	v_pk_add_f32 v[80:81], v[80:81], v[90:91]
	s_nop 1
	v_mov_b32_dpp v90, v80 row_shl:4 row_mask:0xf bank_mask:0x5
	s_nop 1
	v_mov_b32_dpp v90, v80 row_shr:4 row_mask:0xf bank_mask:0xa
	s_nop 1
	v_mov_b32_dpp v91, v81 row_shl:4 row_mask:0xf bank_mask:0x5
	s_nop 1
	v_mov_b32_dpp v91, v81 row_shr:4 row_mask:0xf bank_mask:0xa
	v_pk_fma_f32 v[82:83], v[116:117], v[116:117], v[82:83]
	v_pk_mul_f32 v[70:71], v[146:147], v[92:93]
	v_pk_mul_f32 v[68:69], v[148:149], v[94:95]
	s_waitcnt lgkmcnt(0)
	v_pk_add_f32 v[80:81], v[80:81], v[90:91]
	s_nop 1
	v_mov_b32_dpp v90, v80 row_shl:8 row_mask:0xf bank_mask:0x3
	s_nop 1
	v_mov_b32_dpp v90, v80 row_shr:8 row_mask:0xf bank_mask:0xc
	s_nop 1
	v_mov_b32_dpp v91, v81 row_shl:8 row_mask:0xf bank_mask:0x3
	s_nop 1
	v_mov_b32_dpp v91, v81 row_shr:8 row_mask:0xf bank_mask:0xc
	s_waitcnt lgkmcnt(0)
	v_pk_add_f32 v[80:81], v[80:81], v[90:91]
	s_nop 1
	v_mov_b32_dpp v90, v82 quad_perm:[1,0,3,2] row_mask:0xf bank_mask:0xf
	s_nop 1
	v_mov_b32_dpp v91, v83 quad_perm:[1,0,3,2] row_mask:0xf bank_mask:0xf
	v_pk_add_f32 v[80:81], v[80:81], s[4:5] op_sel_hi:[1,0]
	s_waitcnt lgkmcnt(0)
	v_pk_add_f32 v[82:83], v[82:83], v[90:91]
	s_nop 1
	v_mov_b32_dpp v90, v82 quad_perm:[2,3,0,1] row_mask:0xf bank_mask:0xf
	s_nop 1
	v_mov_b32_dpp v91, v83 quad_perm:[2,3,0,1] row_mask:0xf bank_mask:0xf
	v_mul_f32_e32 v0, 0x4b800000, v80
	v_cmp_gt_f32_e64 s[0:1], s29, v80
	v_cmp_gt_f32_e32 vcc, s29, v81
	s_waitcnt lgkmcnt(0)
	v_pk_add_f32 v[82:83], v[82:83], v[90:91]
	s_nop 1
	v_mov_b32_dpp v90, v82 row_shl:4 row_mask:0xf bank_mask:0x5
	s_nop 1
	v_mov_b32_dpp v90, v82 row_shr:4 row_mask:0xf bank_mask:0xa
	s_nop 1
	v_mov_b32_dpp v91, v83 row_shl:4 row_mask:0xf bank_mask:0x5
	s_nop 1
	v_mov_b32_dpp v91, v83 row_shr:4 row_mask:0xf bank_mask:0xa
	v_cndmask_b32_e64 v0, v80, v0, s[0:1]
	v_rsq_f32_e32 v80, v0
	s_waitcnt lgkmcnt(0)
	v_pk_add_f32 v[82:83], v[82:83], v[90:91]
	s_nop 1
	v_mov_b32_dpp v90, v82 row_shl:8 row_mask:0xf bank_mask:0x3
	s_nop 1
	v_mov_b32_dpp v90, v82 row_shr:8 row_mask:0xf bank_mask:0xc
	s_nop 1
	v_mov_b32_dpp v91, v83 row_shl:8 row_mask:0xf bank_mask:0x3
	s_nop 1
	v_mov_b32_dpp v91, v83 row_shr:8 row_mask:0xf bank_mask:0xc
	s_waitcnt lgkmcnt(0)
	v_pk_add_f32 v[82:83], v[82:83], v[90:91]
	s_nop 0
	v_pk_add_f32 v[82:83], v[82:83], s[4:5] op_sel_hi:[1,0]
	s_mov_b32 s4, 0x45800000
	v_mul_f32_e32 v0, 0x4b800000, v82
	v_cmp_gt_f32_e64 s[42:43], s29, v82
	v_cmp_gt_f32_e64 s[40:41], s29, v83
	s_nop 0
	v_cndmask_b32_e64 v0, v82, v0, s[42:43]
	v_rsq_f32_e32 v82, v0
	v_mul_f32_e32 v0, 0x4b800000, v83
	v_cndmask_b32_e64 v0, v83, v0, s[40:41]
	v_rsq_f32_e32 v83, v0
	v_mul_f32_e32 v0, 0x4b800000, v81
	v_cndmask_b32_e32 v0, v81, v0, vcc
	v_rsq_f32_e32 v81, v0
	v_pk_mul_f32 v[90:91], v[82:83], s[4:5] op_sel_hi:[1,0]
	s_nop 0
	v_cndmask_b32_e64 v83, v83, v91, s[40:41]
	v_cndmask_b32_e64 v82, v82, v90, s[42:43]
	v_pk_mul_f32 v[90:91], v[80:81], s[4:5] op_sel_hi:[1,0]
	v_pk_mul_f32 v[140:141], v[2:3], v[82:83]
	v_cndmask_b32_e32 v81, v81, v91, vcc
	v_cndmask_b32_e64 v80, v80, v90, s[0:1]
	v_pk_mul_f32 v[128:129], v[88:89], v[80:81]
	v_pk_mul_f32 v[130:131], v[130:131], v[80:81]
	v_pk_mul_f32 v[126:127], v[84:85], v[80:81]
	v_pk_mul_f32 v[92:93], v[86:87], v[140:141]
	v_pk_mul_f32 v[90:91], v[134:135], v[128:129]
	v_pk_mul_f32 v[138:139], v[100:101], v[82:83]
	v_pk_mul_f32 v[86:87], v[132:133], v[130:131]
	v_pk_mul_f32 v[136:137], v[118:119], v[82:83]
	v_pk_mul_f32 v[132:133], v[114:115], v[80:81]
	v_pk_mul_f32 v[134:135], v[116:117], v[82:83]
	v_pk_mul_f32 v[88:89], v[108:109], v[138:139]
	v_pk_mul_f32 v[84:85], v[120:121], v[136:137]
	v_pk_mul_f32 v[80:81], v[112:113], v[132:133]
	v_pk_mul_f32 v[2:3], v[110:111], v[134:135]
	v_pk_mul_f32 v[82:83], v[104:105], v[126:127]

.LBB0_856:
	s_or_b64 exec, exec, s[0:1]
	v_bfe_u32 v108, v196, 6, 1
	v_ashrrev_i32_e32 v110, 7, v196
	s_mov_b32 s0, 0x13000
	v_mad_u32_u24 v94, v108, s0, 0
	v_lshlrev_b32_e32 v95, 12, v110
	v_lshlrev_b32_e32 v109, 2, v199
	s_waitcnt lgkmcnt(0)
	s_barrier
	v_add3_u32 v111, v94, v95, v109
	ds_read2st64_b32 v[94:95], v111 offset0:192 offset1:193
	ds_read2st64_b32 v[96:97], v111 offset0:194 offset1:195
	v_lshlrev_b32_e32 v144, 10, v108
	v_readlane_b32 s0, v254, 53
	v_ashrrev_i32_e32 v0, 8, v196
	s_waitcnt lgkmcnt(1)
	v_add_f32_e32 v95, v94, v95
	s_waitcnt lgkmcnt(0)
	v_add_f32_e32 v112, v96, v95
	v_add_f32_e32 v113, v97, v112
	ds_read2st64_b32 v[96:97], v111 offset0:196 offset1:197
	v_cmp_eq_u32_e32 vcc, 1, v0
	v_lshlrev_b32_e32 v166, 2, v192
	s_waitcnt lgkmcnt(0)
	v_add_f32_e32 v114, v96, v113
	v_add_f32_e32 v115, v97, v114
	ds_read2st64_b32 v[96:97], v111 offset0:198 offset1:199
	s_waitcnt lgkmcnt(0)
	v_add_f32_e32 v116, v96, v115
	v_add_f32_e32 v117, v97, v116
	ds_read2st64_b32 v[96:97], v111 offset0:200 offset1:201
	s_waitcnt lgkmcnt(0)
	v_add_f32_e32 v118, v96, v117
	v_add_f32_e32 v119, v97, v118
	ds_read2st64_b32 v[96:97], v111 offset0:202 offset1:203
	s_waitcnt lgkmcnt(0)
	v_add_f32_e32 v120, v96, v119
	v_add_f32_e32 v121, v97, v120
	ds_read2st64_b32 v[96:97], v111 offset0:204 offset1:205
	s_waitcnt lgkmcnt(0)
	v_add_f32_e32 v122, v96, v121
	v_add_f32_e32 v123, v97, v122
	ds_read2st64_b32 v[96:97], v111 offset0:206 offset1:207
	s_waitcnt lgkmcnt(0)
	v_add_f32_e32 v142, v96, v123
	v_add_f32_e32 v143, v97, v142
	v_lshlrev_b32_e32 v96, 8, v110
	v_add_u32_e32 v97, s0, v144
	v_add3_u32 v96, v97, v96, v109
	ds_write_b32 v96, v143
	s_and_saveexec_b64 s[0:1], vcc
	s_cbranch_execz .LBB0_865
	v_lshlrev_b32_e32 v96, 10, v194
	v_lshl_or_b32 v96, v198, 12, v96
	s_add_i32 s4, 0, 0x11000
	v_add3_u32 v145, s4, v166, v96
	ds_read2_b32 v[98:99], v145 offset1:16
	ds_read2_b32 v[104:105], v145 offset0:64 offset1:80
	ds_read2_b32 v[146:147], v145 offset0:32 offset1:48
	ds_read2_b32 v[100:101], v145 offset0:128 offset1:144
	ds_read2_b32 v[96:97], v145 offset0:192 offset1:208
	s_waitcnt lgkmcnt(4)
	v_fma_f32 v148, v68, v98, 0
	v_fmac_f32_e32 v148, v64, v99
	s_waitcnt lgkmcnt(2)
	v_fmac_f32_e32 v148, v72, v146
	v_and_b32_e32 v146, 64, v179
	ds_read2_b32 v[106:107], v145 offset0:96 offset1:112
	ds_read2_b32 v[102:103], v145 offset0:160 offset1:176
	ds_read2_b32 v[98:99], v145 offset0:224 offset1:240
	v_xor_b32_e32 v145, 1, v179
	v_add_u32_e32 v149, 64, v146
	v_cmp_lt_i32_e32 vcc, v145, v149
	v_fmac_f32_e32 v148, v76, v147
	v_xor_b32_e32 v146, 2, v179
	v_cndmask_b32_e32 v145, v179, v145, vcc
	v_lshlrev_b32_e32 v145, 2, v145
	s_nop 1
	v_mov_b32_dpp v147, v148 quad_perm:[1,0,3,2] row_mask:0xf bank_mask:0xf
	v_cmp_lt_i32_e32 vcc, v146, v149
	v_xor_b32_e32 v153, 8, v179
	v_readlane_b32 s4, v254, 59
	v_cndmask_b32_e32 v146, v179, v146, vcc
	v_lshlrev_b32_e32 v146, 2, v146
	s_waitcnt lgkmcnt(0)
	v_add_f32_e32 v148, v148, v147
	s_nop 1
	v_mov_b32_dpp v152, v148 quad_perm:[2,3,0,1] row_mask:0xf bank_mask:0xf
	v_xor_b32_e32 v147, 4, v179
	v_cmp_lt_i32_e32 vcc, v147, v149
	s_waitcnt lgkmcnt(0)
	v_add_f32_e32 v148, v148, v152
	v_cndmask_b32_e32 v147, v179, v147, vcc
	v_lshlrev_b32_e32 v147, 2, v147
	s_nop 1
	v_mov_b32_dpp v152, v148 row_shl:4 row_mask:0xf bank_mask:0x5
	s_nop 1
	v_mov_b32_dpp v152, v148 row_shr:4 row_mask:0xf bank_mask:0xa
	v_cmp_lt_i32_e32 vcc, v153, v149
	s_waitcnt lgkmcnt(0)
	v_add_f32_e32 v152, v148, v152
	v_cndmask_b32_e32 v149, v179, v153, vcc
	v_lshlrev_b32_e32 v149, 2, v149
	s_nop 1
	v_mov_b32_dpp v153, v152 row_shl:8 row_mask:0xf bank_mask:0x3
	s_nop 1
	v_mov_b32_dpp v153, v152 row_shr:8 row_mask:0xf bank_mask:0xc
	v_lshl_add_u32 v148, v198, 6, s4
	v_cmp_eq_u32_e32 vcc, 0, v192
	v_add_u32_e32 v148, v148, v200
	s_and_saveexec_b64 s[24:25], vcc
	s_cbranch_execz .LBB0_859
	s_waitcnt lgkmcnt(0)
	v_add_f32_e32 v152, v152, v153
	ds_write_b32 v148, v152
.LBB0_859:
	s_or_b64 exec, exec, s[24:25]
	v_fma_f32 v104, v69, v104, 0
	v_fmac_f32_e32 v104, v65, v105
	v_fmac_f32_e32 v104, v73, v106
	v_fmac_f32_e32 v104, v77, v107
	s_nop 1
	v_mov_b32_dpp v105, v104 quad_perm:[1,0,3,2] row_mask:0xf bank_mask:0xf
	s_waitcnt lgkmcnt(0)
	v_add_f32_e32 v104, v104, v105
	s_nop 1
	v_mov_b32_dpp v105, v104 quad_perm:[2,3,0,1] row_mask:0xf bank_mask:0xf
	s_waitcnt lgkmcnt(0)
	v_add_f32_e32 v104, v104, v105
	s_nop 1
	v_mov_b32_dpp v105, v104 row_shl:4 row_mask:0xf bank_mask:0x5
	s_nop 1
	v_mov_b32_dpp v105, v104 row_shr:4 row_mask:0xf bank_mask:0xa
	s_waitcnt lgkmcnt(0)
	v_add_f32_e32 v104, v104, v105
	s_nop 1
	v_mov_b32_dpp v105, v104 row_shl:8 row_mask:0xf bank_mask:0x3
	s_nop 1
	v_mov_b32_dpp v105, v104 row_shr:8 row_mask:0xf bank_mask:0xc
	s_and_saveexec_b64 s[24:25], vcc
	s_cbranch_execz .LBB0_861
	s_waitcnt lgkmcnt(0)
	v_add_f32_e32 v104, v104, v105
	ds_write_b32 v148, v104 offset:4
.LBB0_861:
	s_or_b64 exec, exec, s[24:25]
	v_fma_f32 v100, v70, v100, 0
	v_fmac_f32_e32 v100, v66, v101
	v_fmac_f32_e32 v100, v74, v102
	v_fmac_f32_e32 v100, v78, v103
	s_nop 1
	v_mov_b32_dpp v101, v100 quad_perm:[1,0,3,2] row_mask:0xf bank_mask:0xf
	s_waitcnt lgkmcnt(0)
	v_add_f32_e32 v100, v100, v101
	s_nop 1
	v_mov_b32_dpp v101, v100 quad_perm:[2,3,0,1] row_mask:0xf bank_mask:0xf
	s_waitcnt lgkmcnt(0)
	v_add_f32_e32 v100, v100, v101
	s_nop 1
	v_mov_b32_dpp v101, v100 row_shl:4 row_mask:0xf bank_mask:0x5
	s_nop 1
	v_mov_b32_dpp v101, v100 row_shr:4 row_mask:0xf bank_mask:0xa
	s_waitcnt lgkmcnt(0)
	v_add_f32_e32 v100, v100, v101
	s_nop 1
	v_mov_b32_dpp v101, v100 row_shl:8 row_mask:0xf bank_mask:0x3
	s_nop 1
	v_mov_b32_dpp v101, v100 row_shr:8 row_mask:0xf bank_mask:0xc
	s_and_saveexec_b64 s[24:25], vcc
	s_cbranch_execz .LBB0_863
	s_waitcnt lgkmcnt(0)
	v_add_f32_e32 v100, v100, v101
	ds_write_b32 v148, v100 offset:8
.LBB0_863:
	s_or_b64 exec, exec, s[24:25]
	v_fma_f32 v96, v71, v96, 0
	v_fmac_f32_e32 v96, v67, v97
	v_fmac_f32_e32 v96, v75, v98
	v_fmac_f32_e32 v96, v79, v99
	s_nop 1
	v_mov_b32_dpp v97, v96 quad_perm:[1,0,3,2] row_mask:0xf bank_mask:0xf
	s_waitcnt lgkmcnt(0)
	v_add_f32_e32 v96, v96, v97
	s_nop 1
	v_mov_b32_dpp v97, v96 quad_perm:[2,3,0,1] row_mask:0xf bank_mask:0xf
	s_waitcnt lgkmcnt(0)
	v_add_f32_e32 v96, v96, v97
	s_nop 1
	v_mov_b32_dpp v97, v96 row_shl:4 row_mask:0xf bank_mask:0x5
	s_nop 1
	v_mov_b32_dpp v97, v96 row_shr:4 row_mask:0xf bank_mask:0xa
	s_waitcnt lgkmcnt(0)
	v_add_f32_e32 v96, v96, v97
	s_nop 1
	v_mov_b32_dpp v97, v96 row_shl:8 row_mask:0xf bank_mask:0x3
	s_nop 1
	v_mov_b32_dpp v97, v96 row_shr:8 row_mask:0xf bank_mask:0xc
	s_and_b64 exec, exec, vcc
	s_cbranch_execz .LBB0_865
	s_waitcnt lgkmcnt(0)
	v_add_f32_e32 v96, v96, v97
	ds_write_b32 v148, v96 offset:12

.LBB0_886:
	s_or_b64 exec, exec, s[0:1]
	v_or_b32_e32 v147, 3, v144
	v_lshlrev_b32_e32 v104, 8, v147
	v_add3_u32 v156, 0, v104, v166
	ds_read_b32 v112, v156 offset:49152
	v_lshlrev_b32_e32 v104, 3, v147
	v_lshlrev_b32_e32 v157, 6, v147
	v_bitop3_b32 v111, v104, 56, v192 bitop3:0x48
	s_and_saveexec_b64 s[0:1], s[38:39]
	s_xor_b64 s[0:1], exec, s[0:1]
	s_cbranch_execz .LBB0_888
	s_waitcnt lgkmcnt(0)
	ds_read_b32 v106, v156 offset:48896
	s_waitcnt lgkmcnt(1)
	v_mul_f32_e32 v107, 0xbfb8aa3b, v112
	v_exp_f32_e32 v107, v107
	v_or3_b32 v110, v111, v157, v173
	v_lshl_add_u32 v110, v110, 1, 0
	s_waitcnt lgkmcnt(0)
	v_mul_f32_e32 v106, 0x3fb8aa3b, v106
	v_exp_f32_e32 v106, v106
	s_nop 0
	v_mul_f32_e32 v106, v129, v106
	v_cvt_pk_bf16_f32 v106, v106, v106
	ds_write_b16 v110, v106
	v_mul_f32_e32 v106, v71, v107
	v_cvt_pk_bf16_f32 v106, v106, v106
	v_mul_f32_e32 v107, v91, v107
	v_cvt_pk_bf16_f32 v107, v107, v107
	ds_write_b16 v110, v106 offset:8192
	ds_write_b16 v110, v107 offset:16384
.LBB0_888:
	s_or_saveexec_b64 s[0:1], s[0:1]
	v_and_b32_e32 v107, 7, v147
	s_waitcnt lgkmcnt(0)
	v_lshlrev_b32_e32 v106, 7, v147
	v_lshlrev_b32_e32 v107, 1, v107
	s_xor_b64 exec, exec, s[0:1]
	s_cbranch_execz .LBB0_890
	s_waitcnt lgkmcnt(0)
	v_mul_f32_e32 v112, 0x3fb8aa3b, v112
	v_exp_f32_e32 v112, v112
	v_add3_u32 v110, v110, v97, v107
	v_lshl_add_u32 v111, v111, 1, 0
	v_cvt_pk_bf16_f32 v113, v129, v129
	ds_write_b16 v110, v113 offset:40960
	v_mul_f32_e32 v110, v91, v112
	v_add3_u32 v111, v111, v106, v95
	v_cvt_pk_bf16_f32 v110, v110, v110
	ds_write_b16 v111, v110 offset:24576

.LBB0_966:
	s_or_b64 exec, exec, s[0:1]
	ds_read_b32 v122, v102 offset:64
	v_bitop3_b32 v90, v103, 40, v192 bitop3:0xc8
	s_and_saveexec_b64 s[0:1], s[38:39]
	s_xor_b64 s[0:1], exec, s[0:1]
	s_cbranch_execz .LBB0_968
	s_waitcnt lgkmcnt(0)
	v_lshlrev_b32_e32 v123, 2, v154
	s_movk_i32 s4, 0xff00
	v_add3_u32 v123, v101, v123, s4
	ds_read_b32 v123, v123
	s_waitcnt lgkmcnt(1)
	v_mul_f32_e32 v122, 0xbfb8aa3b, v122
	v_exp_f32_e32 v122, v122
	v_or3_b32 v90, v90, v82, v173
	v_lshl_add_u32 v90, v90, 1, 0
	s_waitcnt lgkmcnt(0)
	v_mul_f32_e32 v123, 0x3fb8aa3b, v123
	v_exp_f32_e32 v123, v123
	v_add_u32_e32 v167, 0x13000, v90
	v_mul_f32_e32 v123, v138, v123
	v_cvt_pk_bf16_f32 v123, v123, v123
	ds_write_b16 v167, v123
	v_mul_f32_e32 v123, v65, v122
	v_mul_f32_e32 v122, v88, v122
	v_cvt_pk_bf16_f32 v122, v122, v122
	v_add_u32_e32 v167, 0x15000, v90
	v_add_u32_e32 v90, 0x17000, v90
	v_cvt_pk_bf16_f32 v123, v123, v123
	ds_write_b16 v167, v123
	ds_write_b16 v90, v122

.LBB0_970:
	s_or_b64 exec, exec, s[0:1]
	ds_read_b32 v90, v109 offset:64
	v_bitop3_b32 v88, v110, 56, v154 bitop3:0x48
	s_and_saveexec_b64 s[0:1], s[38:39]
	s_xor_b64 s[0:1], exec, s[0:1]
	s_cbranch_execz .LBB0_972
	s_waitcnt lgkmcnt(0)
	v_lshlrev_b32_e32 v122, 2, v154
	s_movk_i32 s4, 0xff00
	v_add3_u32 v122, v108, v122, s4
	ds_read_b32 v122, v122
	s_waitcnt lgkmcnt(1)
	v_mul_f32_e32 v90, 0xbfb8aa3b, v90
	v_exp_f32_e32 v90, v90
	v_or3_b32 v88, v88, v106, v173
	v_lshl_add_u32 v88, v88, 1, 0
	s_waitcnt lgkmcnt(0)
	v_mul_f32_e32 v122, 0x3fb8aa3b, v122
	v_exp_f32_e32 v122, v122
	v_add_u32_e32 v123, 0x13000, v88
	v_mul_f32_e32 v89, v89, v90
	v_cvt_pk_bf16_f32 v89, v89, v89
	v_mul_f32_e32 v122, v139, v122
	v_cvt_pk_bf16_f32 v122, v122, v122
	ds_write_b16 v123, v122
	v_mul_f32_e32 v122, v66, v90
	v_add_u32_e32 v90, 0x15000, v88
	v_add_u32_e32 v88, 0x17000, v88
	ds_write_b16 v88, v89
	v_cvt_pk_bf16_f32 v122, v122, v122
	ds_write_b16 v90, v122

.LBB0_984:
	s_or_b64 exec, exec, s[0:1]
	ds_read_b32 v88, v102 offset:128
	v_bitop3_b32 v86, v103, 56, v151 bitop3:0x48
	s_and_saveexec_b64 s[0:1], s[38:39]
	s_xor_b64 s[0:1], exec, s[0:1]
	s_cbranch_execz .LBB0_986
	s_waitcnt lgkmcnt(0)
	v_lshlrev_b32_e32 v89, 2, v151
	s_movk_i32 s4, 0xff00
	v_add3_u32 v89, v101, v89, s4
	ds_read_b32 v89, v89
	s_waitcnt lgkmcnt(1)
	v_mul_f32_e32 v88, 0xbfb8aa3b, v88
	v_exp_f32_e32 v88, v88
	v_or3_b32 v86, v86, v82, v173
	v_lshl_add_u32 v86, v86, 1, 0
	s_waitcnt lgkmcnt(0)
	v_mul_f32_e32 v89, 0x3fb8aa3b, v89
	v_exp_f32_e32 v89, v89
	v_add_u32_e32 v90, 0x13000, v86
	v_mul_f32_e32 v89, v136, v89
	v_cvt_pk_bf16_f32 v89, v89, v89
	ds_write_b16 v90, v89
	v_mul_f32_e32 v89, v73, v88
	v_mul_f32_e32 v88, v84, v88
	v_cvt_pk_bf16_f32 v88, v88, v88
	v_add_u32_e32 v90, 0x15000, v86
	v_add_u32_e32 v86, 0x17000, v86
	v_cvt_pk_bf16_f32 v89, v89, v89
	ds_write_b16 v90, v89
	ds_write_b16 v86, v88

.LBB0_988:
	s_or_b64 exec, exec, s[0:1]
	ds_read_b32 v86, v109 offset:128
	v_bitop3_b32 v84, v110, 40, v151 bitop3:0x48
	s_and_saveexec_b64 s[0:1], s[38:39]
	s_xor_b64 s[0:1], exec, s[0:1]
	s_cbranch_execz .LBB0_990
	s_waitcnt lgkmcnt(0)
	v_lshlrev_b32_e32 v88, 2, v151
	s_movk_i32 s4, 0xff00
	v_add3_u32 v88, v108, v88, s4
	ds_read_b32 v88, v88
	s_waitcnt lgkmcnt(1)
	v_mul_f32_e32 v86, 0xbfb8aa3b, v86
	v_exp_f32_e32 v86, v86
	v_or3_b32 v84, v84, v106, v173
	v_lshl_add_u32 v84, v84, 1, 0
	s_waitcnt lgkmcnt(0)
	v_mul_f32_e32 v88, 0x3fb8aa3b, v88
	v_exp_f32_e32 v88, v88
	v_add_u32_e32 v89, 0x13000, v84
	v_mul_f32_e32 v85, v85, v86
	v_cvt_pk_bf16_f32 v85, v85, v85
	v_mul_f32_e32 v88, v137, v88
	v_cvt_pk_bf16_f32 v88, v88, v88
	ds_write_b16 v89, v88
	v_mul_f32_e32 v88, v74, v86
	v_add_u32_e32 v86, 0x15000, v84
	v_add_u32_e32 v84, 0x17000, v84
	ds_write_b16 v84, v85
	v_cvt_pk_bf16_f32 v88, v88, v88
	ds_write_b16 v86, v88

.LBB0_1002:
	s_or_b64 exec, exec, s[0:1]
	ds_read_b32 v84, v102 offset:192
	v_bitop3_b32 v80, v103, 40, v150 bitop3:0x48
	s_and_saveexec_b64 s[0:1], s[38:39]
	s_xor_b64 s[0:1], exec, s[0:1]
	s_cbranch_execz .LBB0_1004
	s_waitcnt lgkmcnt(0)
	v_lshlrev_b32_e32 v85, 2, v150
	s_movk_i32 s4, 0xff00
	v_add3_u32 v85, v101, v85, s4
	ds_read_b32 v85, v85
	s_waitcnt lgkmcnt(1)
	v_mul_f32_e32 v84, 0xbfb8aa3b, v84
	v_or3_b32 v80, v80, v82, v173
	v_exp_f32_e32 v82, v84
	v_lshl_add_u32 v80, v80, 1, 0
	s_waitcnt lgkmcnt(0)
	v_mul_f32_e32 v84, 0x3fb8aa3b, v85
	v_exp_f32_e32 v84, v84
	v_add_u32_e32 v85, 0x13000, v80
	v_mul_f32_e32 v86, v77, v82
	v_mul_f32_e32 v82, v2, v82
	v_mul_f32_e32 v84, v134, v84
	v_cvt_pk_bf16_f32 v84, v84, v84
	ds_write_b16 v85, v84
	v_add_u32_e32 v84, 0x15000, v80
	v_add_u32_e32 v80, 0x17000, v80
	v_cvt_pk_bf16_f32 v86, v86, v86
	v_cvt_pk_bf16_f32 v82, v82, v82
	ds_write_b16 v84, v86
	ds_write_b16 v80, v82

.LBB0_1048:
	v_lshlrev_b32_e32 v0, 2, v193
	v_lshl_add_u64 v[2:3], v[88:89], 0, v[0:1]
	v_lshlrev_b32_e32 v0, 2, v92
	v_lshl_add_u64 v[2:3], v[2:3], 0, v[0:1]
	global_load_dwordx4 v[80:83], v[2:3], off offset:16
	global_load_dwordx4 v[84:87], v[2:3], off
	s_mov_b64 s[0:1], 0x1000
	v_add_co_u32_e32 v116, vcc, s21, v2
	v_lshl_add_u64 v[104:105], v[2:3], 0, s[0:1]
	s_nop 0
	v_addc_co_u32_e32 v117, vcc, 0, v3, vcc
	s_movk_i32 s0, 0x2000
	v_add_co_u32_e32 v120, vcc, s0, v2
	s_mov_b64 s[0:1], 0x1080
	s_nop 0
	v_addc_co_u32_e32 v121, vcc, 0, v3, vcc
	v_lshl_add_u64 v[118:119], v[2:3], 0, s[0:1]
	s_mov_b64 s[0:1], 0x2000
	s_waitcnt vmcnt(0)
	v_cvt_pk_bf16_f32 v84, v84, v85
	v_cvt_pk_bf16_f32 v85, v86, v87
	v_cvt_pk_bf16_f32 v86, v80, v81
	v_cvt_pk_bf16_f32 v87, v82, v83
	global_load_dwordx4 v[80:83], v[2:3], off offset:144
	global_load_dwordx4 v[88:91], v[2:3], off offset:128
	ds_read_b128 v[108:111], v171 offset:24576
	ds_read_b128 v[112:115], v172 offset:24576
	s_waitcnt vmcnt(0)
	v_cvt_pk_bf16_f32 v88, v88, v89
	v_cvt_pk_bf16_f32 v89, v90, v91
	v_cvt_pk_bf16_f32 v90, v80, v81
	v_cvt_pk_bf16_f32 v91, v82, v83
	s_waitcnt lgkmcnt(1)
	v_mfma_f32_16x16x32_bf16 v[80:83], v[108:111], v[84:87], 0
	ds_read_b128 v[96:99], v171 offset:32768
	ds_read_b128 v[84:87], v169 offset:40960
	s_waitcnt lgkmcnt(2)
	v_mfma_f32_16x16x32_bf16 v[80:83], v[112:115], v[88:91], v[80:83]
	s_waitcnt lgkmcnt(0)
	v_mfma_f32_16x16x32_bf16 v[80:83], v[96:99], v[84:87], v[80:83]
	ds_read_b128 v[92:95], v172 offset:32768
	ds_read_b128 v[84:87], v168 offset:40960
	s_waitcnt lgkmcnt(0)
	v_mfma_f32_16x16x32_bf16 v[80:83], v[92:95], v[84:87], v[80:83]
	ds_read_b128 v[88:91], v171 offset:16384
	ds_read_b128 v[84:87], v169 offset:8192
	s_waitcnt lgkmcnt(0)
	v_mfma_f32_16x16x32_bf16 v[80:83], v[88:91], v[84:87], v[80:83]
	ds_read_b128 v[84:87], v172 offset:16384
	ds_read_b128 v[100:103], v168 offset:8192
	s_waitcnt lgkmcnt(0)
	v_mfma_f32_16x16x32_bf16 v[80:83], v[84:87], v[100:103], v[80:83]
	global_load_dwordx4 v[100:103], v[120:121], off offset:-4096
	s_nop 0
	global_load_dwordx4 v[104:107], v[104:105], off offset:16
	s_waitcnt vmcnt(1)
	v_cvt_pk_bf16_f32 v100, v100, v101
	v_cvt_pk_bf16_f32 v101, v102, v103
	s_waitcnt vmcnt(0)
	v_cvt_pk_bf16_f32 v102, v104, v105
	v_cvt_pk_bf16_f32 v103, v106, v107
	global_load_dwordx4 v[104:107], v[116:117], off offset:128
	s_nop 0
	global_load_dwordx4 v[116:119], v[118:119], off offset:16
	v_mfma_f32_16x16x32_bf16 v[100:103], v[108:111], v[100:103], 0
	s_waitcnt vmcnt(1)
	v_cvt_pk_bf16_f32 v104, v104, v105
	v_cvt_pk_bf16_f32 v105, v106, v107
	s_waitcnt vmcnt(0)
	v_cvt_pk_bf16_f32 v106, v116, v117
	v_cvt_pk_bf16_f32 v107, v118, v119
	v_lshl_add_u64 v[116:117], v[2:3], 0, s[0:1]
	v_mfma_f32_16x16x32_bf16 v[100:103], v[112:115], v[104:107], v[100:103]
	ds_read_b128 v[104:107], v169 offset:43008
	s_mov_b64 s[0:1], 0x2080
	v_lshl_add_u64 v[122:123], v[2:3], 0, s[0:1]
	s_waitcnt lgkmcnt(0)
	v_mfma_f32_16x16x32_bf16 v[100:103], v[96:99], v[104:107], v[100:103]
	ds_read_b128 v[104:107], v168 offset:43008
	s_mov_b64 s[0:1], 0x3000
	s_waitcnt lgkmcnt(0)
	v_mfma_f32_16x16x32_bf16 v[100:103], v[92:95], v[104:107], v[100:103]
	ds_read_b128 v[104:107], v169 offset:10240
	s_waitcnt lgkmcnt(0)
	v_mfma_f32_16x16x32_bf16 v[100:103], v[88:91], v[104:107], v[100:103]
	ds_read_b128 v[104:107], v168 offset:10240
	s_waitcnt lgkmcnt(0)
	v_mfma_f32_16x16x32_bf16 v[100:103], v[84:87], v[104:107], v[100:103]
	global_load_dwordx4 v[104:107], v[120:121], off
	s_nop 0
	global_load_dwordx4 v[116:119], v[116:117], off offset:16
	s_waitcnt vmcnt(1)
	v_cvt_pk_bf16_f32 v104, v104, v105
	v_cvt_pk_bf16_f32 v105, v106, v107
	s_waitcnt vmcnt(0)
	v_cvt_pk_bf16_f32 v106, v116, v117
	v_cvt_pk_bf16_f32 v107, v118, v119
	global_load_dwordx4 v[116:119], v[120:121], off offset:128
	s_nop 0
	global_load_dwordx4 v[120:123], v[122:123], off offset:16
	v_mfma_f32_16x16x32_bf16 v[104:107], v[108:111], v[104:107], 0
	s_waitcnt vmcnt(1)
	v_cvt_pk_bf16_f32 v116, v116, v117
	v_cvt_pk_bf16_f32 v117, v118, v119
	s_waitcnt vmcnt(0)
	v_cvt_pk_bf16_f32 v118, v120, v121
	v_cvt_pk_bf16_f32 v119, v122, v123
	v_lshl_add_u64 v[120:121], v[2:3], 0, s[0:1]
	v_mfma_f32_16x16x32_bf16 v[104:107], v[112:115], v[116:119], v[104:107]
	ds_read_b128 v[116:119], v169 offset:45056
	s_movk_i32 s0, 0x3000
	v_add_co_u32_e32 v142, vcc, s0, v2
	s_waitcnt lgkmcnt(0)
	v_mfma_f32_16x16x32_bf16 v[104:107], v[96:99], v[116:119], v[104:107]
	ds_read_b128 v[116:119], v168 offset:45056
	v_addc_co_u32_e32 v143, vcc, 0, v3, vcc
	s_waitcnt lgkmcnt(0)
	v_mfma_f32_16x16x32_bf16 v[104:107], v[92:95], v[116:119], v[104:107]
	ds_read_b128 v[116:119], v169 offset:12288
	s_mov_b64 s[0:1], 0x3080
	v_lshl_add_u64 v[2:3], v[2:3], 0, s[0:1]
	s_waitcnt lgkmcnt(0)
	v_mfma_f32_16x16x32_bf16 v[104:107], v[88:91], v[116:119], v[104:107]
	ds_read_b128 v[116:119], v168 offset:12288
	s_movk_i32 s0, 0xff84
	v_mad_i32_i24 v0, v192, s0, v167
	s_waitcnt lgkmcnt(0)
	v_mfma_f32_16x16x32_bf16 v[104:107], v[84:87], v[116:119], v[104:107]
	global_load_dwordx4 v[116:119], v[142:143], off
	s_nop 0
	global_load_dwordx4 v[120:123], v[120:121], off offset:16
	s_waitcnt vmcnt(1)
	v_cvt_pk_bf16_f32 v116, v116, v117
	v_cvt_pk_bf16_f32 v117, v118, v119
	s_waitcnt vmcnt(0)
	v_cvt_pk_bf16_f32 v118, v120, v121
	v_cvt_pk_bf16_f32 v119, v122, v123
	global_load_dwordx4 v[120:123], v[142:143], off offset:128
	global_load_dwordx4 v[170:173], v[2:3], off offset:16
	v_mfma_f32_16x16x32_bf16 v[108:111], v[108:111], v[116:119], 0
	v_cndmask_b32_e64 v2, v158, v144, s[36:37]
	v_lshl_add_u32 v2, v2, 8, v0
	v_cndmask_b32_e64 v3, v159, v145, s[36:37]
	v_lshl_add_u32 v3, v3, 8, v0
	v_add_u32_e32 v2, 0xc000, v2
	v_add_u32_e32 v3, 0xc000, v3
	s_waitcnt vmcnt(1)
	v_cvt_pk_bf16_f32 v120, v120, v121
	v_cvt_pk_bf16_f32 v121, v122, v123
	s_waitcnt vmcnt(0)
	v_cvt_pk_bf16_f32 v122, v170, v171
	v_cvt_pk_bf16_f32 v123, v172, v173
	s_nop 0
	v_mfma_f32_16x16x32_bf16 v[108:111], v[112:115], v[120:123], v[108:111]
	ds_read_b128 v[112:115], v169 offset:47104
	s_waitcnt lgkmcnt(0)
	v_mfma_f32_16x16x32_bf16 v[96:99], v[96:99], v[112:115], v[108:111]
	s_nop 4
	ds_read_b128 v[108:111], v168 offset:47104
	s_waitcnt lgkmcnt(0)
	v_mfma_f32_16x16x32_bf16 v[92:95], v[92:95], v[108:111], v[96:99]
	s_nop 2
	ds_read_b128 v[96:99], v169 offset:14336
	s_waitcnt lgkmcnt(0)
	v_mfma_f32_16x16x32_bf16 v[88:91], v[88:91], v[96:99], v[92:95]
	s_nop 2
	ds_read_b128 v[92:95], v168 offset:14336
	s_waitcnt lgkmcnt(0)
	s_waitcnt lgkmcnt(0)
	v_mfma_f32_16x16x32_bf16 v[84:87], v[84:87], v[92:95], v[88:91]
	s_nop 2
	v_cndmask_b32_e64 v88, v164, v146, s[36:37]
	v_cndmask_b32_e64 v89, v165, v147, s[36:37]
	v_lshl_add_u32 v88, v88, 8, v0
	v_lshl_add_u32 v0, v89, 8, v0
	s_barrier
	ds_write2_b32 v2, v80, v100 offset1:16
	v_add_u32_e32 v80, 0xc000, v88
	v_add_u32_e32 v0, 0xc000, v0
	ds_write2_b32 v3, v81, v101 offset1:16
	ds_write2_b32 v80, v82, v102 offset1:16
	ds_write2_b32 v0, v83, v103 offset1:16
	ds_write2_b32 v2, v104, v84 offset0:32 offset1:48
	ds_write2_b32 v3, v105, v85 offset0:32 offset1:48
	ds_write2_b32 v80, v106, v86 offset0:32 offset1:48
	ds_write2_b32 v0, v107, v87 offset0:32 offset1:48
	s_waitcnt lgkmcnt(0)
	s_barrier
	s_and_saveexec_b64 s[40:41], s[36:37]
	s_cbranch_execz .LBB0_819
	v_lshlrev_b32_e32 v0, 6, v144
	v_or_b32_e32 v2, v0, v192
	v_lshlrev_b32_e32 v3, 2, v2
	v_add_u32_e32 v2, 0, v3
	v_add_u32_e32 v3, s30, v3
	ds_read_b32 v2, v2 offset:49152
	ds_read_b32 v86, v3
	ds_read_b32 v114, v148 offset:49344
	v_or_b32_e32 v3, v152, v192
	v_lshlrev_b32_e32 v3, 2, v3
	v_add_u32_e32 v80, 0, v3
	v_add_u32_e32 v3, s30, v3
	ds_read_b32 v80, v80 offset:49152
	ds_read_b32 v88, v3
	v_or_b32_e32 v3, v155, v192
	v_lshlrev_b32_e32 v3, 2, v3
	v_add_u32_e32 v81, 0, v3
	v_add_u32_e32 v3, s30, v3
	ds_read_b32 v82, v81 offset:49152
	ds_read_b32 v90, v3
	v_or_b32_e32 v3, v157, v192
	v_lshlrev_b32_e32 v3, 2, v3
	v_add_u32_e32 v81, 0, v3
	v_add_u32_e32 v3, s30, v3
	ds_read_b32 v84, v81 offset:49152
	ds_read_b32 v92, v3
	v_or_b32_e32 v3, v0, v154
	v_lshl_add_u32 v3, v3, 2, s30
	ds_read_b32 v87, v3
	ds_read_b32 v116, v149 offset:49344
	v_or_b32_e32 v3, v152, v154
	v_lshl_add_u32 v3, v3, 2, s30
	ds_read_b32 v89, v3
	ds_read_b32 v110, v153 offset:49344
	v_or_b32_e32 v3, v155, v154
	v_lshl_add_u32 v3, v3, 2, s30
	ds_read_b32 v91, v3
	ds_read_b32 v100, v156 offset:49344
	v_or_b32_e32 v3, v157, v154
	v_lshl_add_u32 v3, v3, 2, s30
	ds_read_b32 v93, v3
	v_or_b32_e32 v3, v0, v151
	v_or_b32_e32 v0, v0, v150
	v_lshl_add_u32 v0, v0, 2, s30
	ds_read_b32 v106, v0
	v_or_b32_e32 v0, v152, v150
	v_lshl_add_u32 v3, v3, 2, s30
	v_lshl_add_u32 v0, v0, 2, s30
	ds_read_b32 v107, v3
	ds_read_b32 v112, v0
	v_or_b32_e32 v3, v152, v151
	v_or_b32_e32 v0, v155, v150
	v_lshl_add_u32 v3, v3, 2, s30
	v_lshl_add_u32 v0, v0, 2, s30
	ds_read_b32 v113, v3
	ds_read_b32 v102, v0
	v_or_b32_e32 v3, v155, v151
	v_or_b32_e32 v0, v157, v150
	v_lshl_add_u32 v3, v3, 2, s30
	v_lshl_add_u32 v0, v0, 2, s30
	ds_read_b32 v103, v3
	ds_read_b32 v96, v0
	v_or_b32_e32 v3, v157, v151
	v_lshl_add_u32 v3, v3, 2, s30
	ds_read_b32 v97, v3
	v_and_b32_e32 v3, 64, v179
	v_xor_b32_e32 v0, 1, v179
	v_add_u32_e32 v3, 64, v3
	v_cmp_lt_i32_e32 vcc, v0, v3
	v_add_u32_e32 v81, 0xc000, v148
	ds_read2_b32 v[104:105], v81 offset0:16 offset1:32
	v_cndmask_b32_e32 v0, v179, v0, vcc
	v_lshlrev_b32_e32 v118, 2, v0
	v_xor_b32_e32 v0, 2, v179
	v_cmp_lt_i32_e32 vcc, v0, v3
	s_waitcnt lgkmcnt(0)
	v_mov_b32_e32 v115, v105
	v_add_u32_e32 v81, 0xc000, v149
	v_cndmask_b32_e32 v0, v179, v0, vcc
	v_lshlrev_b32_e32 v119, 2, v0
	v_xor_b32_e32 v0, 4, v179
	v_cmp_lt_i32_e32 vcc, v0, v3
	v_pk_add_f32 v[114:115], v[114:115], v[106:107]
	ds_read2_b32 v[108:109], v81 offset0:16 offset1:32
	v_cndmask_b32_e32 v0, v179, v0, vcc
	v_lshlrev_b32_e32 v120, 2, v0
	v_xor_b32_e32 v0, 8, v179
	v_cmp_lt_i32_e32 vcc, v0, v3
	v_mov_b32_e32 v3, v104
	v_pk_add_f32 v[2:3], v[2:3], v[86:87]
	v_cndmask_b32_e32 v0, v179, v0, vcc
	v_lshlrev_b32_e32 v121, 2, v0
	v_add_f32_e32 v0, 0, v2
	v_add_f32_e32 v0, v0, v3
	v_add_u32_e32 v81, 0xc000, v153
	v_add_f32_e32 v0, v0, v115
	ds_read2_b32 v[98:99], v81 offset0:16 offset1:32
	v_add_u32_e32 v81, 0xc000, v156
	v_add_f32_e32 v0, v0, v114
	ds_read2_b32 v[94:95], v81 offset0:16 offset1:32
	s_nop 1
	v_mov_b32_dpp v81, v0 quad_perm:[1,0,3,2] row_mask:0xf bank_mask:0xf
	s_waitcnt lgkmcnt(2)
	v_mov_b32_e32 v117, v109
	v_pk_add_f32 v[112:113], v[116:117], v[112:113]
	s_waitcnt lgkmcnt(1)
	v_mov_b32_e32 v111, v99
	v_pk_add_f32 v[102:103], v[110:111], v[102:103]
	s_waitcnt lgkmcnt(0)
	v_add_f32_e32 v0, v0, v81
	s_nop 1
	v_mov_b32_dpp v81, v0 quad_perm:[2,3,0,1] row_mask:0xf bank_mask:0xf
	v_mov_b32_e32 v101, v95
	v_pk_add_f32 v[96:97], v[100:101], v[96:97]
	s_mov_b32 s0, 0x3a27c5ac
	s_mov_b32 s6, 0x3c800000
	s_waitcnt lgkmcnt(0)
	v_add_f32_e32 v0, v0, v81
	s_nop 1
	v_mov_b32_dpp v81, v0 row_shl:4 row_mask:0xf bank_mask:0x5
	s_nop 1
	v_mov_b32_dpp v81, v0 row_shr:4 row_mask:0xf bank_mask:0xa
	v_readlane_b32 s44, v252, 35
	v_readlane_b32 s45, v252, 36
	v_readlane_b32 s46, v252, 37
	v_readlane_b32 s47, v252, 38
	s_waitcnt lgkmcnt(0)
	v_add_f32_e32 v0, v0, v81
	s_nop 1
	v_mov_b32_dpp v81, v0 row_shl:8 row_mask:0xf bank_mask:0x3
	s_nop 1
	v_mov_b32_dpp v81, v0 row_shr:8 row_mask:0xf bank_mask:0xc
	v_readlane_b32 s48, v252, 39
	v_readlane_b32 s49, v252, 40
	v_readlane_b32 s50, v252, 41
	v_readlane_b32 s51, v252, 42
	s_waitcnt lgkmcnt(0)
	v_add_f32_e32 v0, v0, v81
	v_mov_b32_e32 v81, v108
	v_mul_f32_e32 v0, 0x3c800000, v0
	v_pk_add_f32 v[80:81], v[80:81], v[88:89]
	v_pk_add_f32 v[86:87], v[2:3], v[0:1] op_sel_hi:[1,0] neg_lo:[0,1] neg_hi:[0,1]
	v_pk_add_f32 v[2:3], v[114:115], v[0:1] op_sel_hi:[1,0] neg_lo:[0,1] neg_hi:[0,1]
	v_add_f32_e32 v0, 0, v80
	v_add_f32_e32 v0, v0, v81
	v_add_f32_e32 v0, v0, v113
	v_add_f32_e32 v0, v0, v112
	s_nop 1
	v_mov_b32_dpp v83, v0 quad_perm:[1,0,3,2] row_mask:0xf bank_mask:0xf
	v_pk_mul_f32 v[106:107], v[86:87], v[86:87]
	v_pk_mul_f32 v[104:105], v[2:3], v[2:3]
	v_mov_b32_e32 v101, v106
	v_readlane_b32 s52, v252, 43
	s_waitcnt lgkmcnt(0)
	v_add_f32_e32 v0, v0, v83
	s_nop 1
	v_mov_b32_dpp v83, v0 quad_perm:[2,3,0,1] row_mask:0xf bank_mask:0xf
	v_readlane_b32 s53, v252, 44
	v_readlane_b32 s54, v252, 45
	v_readlane_b32 s55, v252, 46
	v_readlane_b32 s56, v252, 47
	s_waitcnt lgkmcnt(0)
	v_add_f32_e32 v0, v0, v83
	s_nop 1
	v_mov_b32_dpp v83, v0 row_shl:4 row_mask:0xf bank_mask:0x5
	s_nop 1
	v_mov_b32_dpp v83, v0 row_shr:4 row_mask:0xf bank_mask:0xa
	v_readlane_b32 s57, v252, 48
	s_mov_b64 s[44:45], s[48:49]
	s_mov_b64 s[46:47], s[50:51]
	s_mov_b64 s[48:49], s[52:53]
	s_waitcnt lgkmcnt(0)
	v_add_f32_e32 v0, v0, v83
	s_nop 1
	v_mov_b32_dpp v83, v0 row_shl:8 row_mask:0xf bank_mask:0x3
	s_nop 1
	v_mov_b32_dpp v83, v0 row_shr:8 row_mask:0xf bank_mask:0xc
	s_mov_b64 s[50:51], s[54:55]
	s_mov_b64 s[52:53], s[56:57]
	v_readlane_b32 s5, v254, 59
	s_lshl_b32 s4, s4, 6
	s_waitcnt lgkmcnt(0)
	v_add_f32_e32 v0, v0, v83
	v_mov_b32_e32 v83, v98
	v_mul_f32_e32 v0, 0x3c800000, v0
	v_pk_add_f32 v[82:83], v[82:83], v[90:91]
	v_pk_add_f32 v[88:89], v[80:81], v[0:1] op_sel_hi:[1,0] neg_lo:[0,1] neg_hi:[0,1]
	v_pk_add_f32 v[80:81], v[112:113], v[0:1] op_sel_hi:[1,0] neg_lo:[0,1] neg_hi:[0,1]
	v_add_f32_e32 v0, 0, v82
	v_add_f32_e32 v0, v0, v83
	v_add_f32_e32 v0, v0, v103
	v_add_f32_e32 v0, v0, v102
	s_nop 1
	v_mov_b32_dpp v85, v0 quad_perm:[1,0,3,2] row_mask:0xf bank_mask:0xf
	v_pk_mul_f32 v[108:109], v[88:89], v[88:89]
	v_pk_mul_f32 v[112:113], v[80:81], v[80:81]
	v_mov_b32_e32 v100, v108
	v_mov_b32_e32 v106, v109
	s_waitcnt lgkmcnt(0)
	v_add_f32_e32 v0, v0, v85
	s_nop 1
	v_mov_b32_dpp v85, v0 quad_perm:[2,3,0,1] row_mask:0xf bank_mask:0xf
	v_pk_add_f32 v[100:101], v[100:101], v[106:107]
	s_add_i32 s4, s4, s63
	v_readlane_b32 s58, v252, 49
	v_readlane_b32 s59, v252, 50
	s_waitcnt lgkmcnt(0)
	v_add_f32_e32 v0, v0, v85
	s_nop 1
	v_mov_b32_dpp v85, v0 row_shl:4 row_mask:0xf bank_mask:0x5
	s_nop 1
	v_mov_b32_dpp v85, v0 row_shr:4 row_mask:0xf bank_mask:0xa
	s_waitcnt lgkmcnt(0)
	v_add_f32_e32 v0, v0, v85
	s_nop 1
	v_mov_b32_dpp v85, v0 row_shl:8 row_mask:0xf bank_mask:0x3
	s_nop 1
	v_mov_b32_dpp v85, v0 row_shr:8 row_mask:0xf bank_mask:0xc
	s_waitcnt lgkmcnt(0)
	v_add_f32_e32 v0, v0, v85
	v_mov_b32_e32 v85, v94
	v_mul_f32_e32 v0, 0x3c800000, v0
	v_pk_add_f32 v[84:85], v[84:85], v[92:93]
	v_pk_add_f32 v[90:91], v[82:83], v[0:1] op_sel_hi:[1,0] neg_lo:[0,1] neg_hi:[0,1]
	v_pk_add_f32 v[82:83], v[102:103], v[0:1] op_sel_hi:[1,0] neg_lo:[0,1] neg_hi:[0,1]
	v_add_f32_e32 v0, 0, v84
	v_add_f32_e32 v0, v0, v85
	v_mov_b32_e32 v102, v113
	v_mov_b32_e32 v103, v105
	v_add_f32_e32 v0, v0, v97
	v_pk_add_f32 v[100:101], v[102:103], v[100:101]
	v_mov_b32_e32 v113, v104
	v_add_f32_e32 v0, v0, v96
	v_pk_add_f32 v[100:101], v[112:113], v[100:101]
	s_nop 1
	v_mov_b32_dpp v92, v0 quad_perm:[1,0,3,2] row_mask:0xf bank_mask:0xf
	s_nop 1
	v_mov_b32_dpp v103, v101 quad_perm:[1,0,3,2] row_mask:0xf bank_mask:0xf
	s_nop 1
	v_mov_b32_dpp v102, v100 quad_perm:[1,0,3,2] row_mask:0xf bank_mask:0xf
	v_mov_b64_e32 v[104:105], s[0:1]
	v_pk_mul_f32 v[98:99], v[90:91], v[90:91]
	s_waitcnt lgkmcnt(0)
	v_add_f32_e32 v0, v0, v92
	s_nop 1
	v_mov_b32_dpp v92, v0 quad_perm:[2,3,0,1] row_mask:0xf bank_mask:0xf
	s_waitcnt lgkmcnt(0)
	v_pk_add_f32 v[100:101], v[100:101], v[102:103]
	s_nop 1
	v_mov_b32_dpp v103, v101 quad_perm:[2,3,0,1] row_mask:0xf bank_mask:0xf
	s_nop 1
	v_mov_b32_dpp v102, v100 quad_perm:[2,3,0,1] row_mask:0xf bank_mask:0xf
	v_pk_mul_f32 v[110:111], v[82:83], v[82:83]
	s_waitcnt lgkmcnt(0)
	v_add_f32_e32 v0, v0, v92
	s_nop 1
	v_mov_b32_dpp v92, v0 row_shl:4 row_mask:0xf bank_mask:0x5
	s_nop 1
	v_mov_b32_dpp v92, v0 row_shr:4 row_mask:0xf bank_mask:0xa
	s_waitcnt lgkmcnt(0)
	v_pk_add_f32 v[100:101], v[100:101], v[102:103]
	s_nop 1
	v_mov_b32_dpp v103, v101 row_shl:4 row_mask:0xf bank_mask:0x5
	s_nop 1
	v_mov_b32_dpp v103, v101 row_shr:4 row_mask:0xf bank_mask:0xa
	s_nop 1
	v_mov_b32_dpp v102, v100 row_shl:4 row_mask:0xf bank_mask:0x5
	s_nop 1
	v_mov_b32_dpp v102, v100 row_shr:4 row_mask:0xf bank_mask:0xa
	s_waitcnt lgkmcnt(0)
	v_add_f32_e32 v0, v0, v92
	s_nop 1
	v_mov_b32_dpp v92, v0 row_shl:8 row_mask:0xf bank_mask:0x3
	s_nop 1
	v_mov_b32_dpp v92, v0 row_shr:8 row_mask:0xf bank_mask:0xc
	s_waitcnt lgkmcnt(0)
	v_pk_add_f32 v[100:101], v[100:101], v[102:103]
	s_nop 1
	v_mov_b32_dpp v103, v101 row_shl:8 row_mask:0xf bank_mask:0x3
	s_nop 1
	v_mov_b32_dpp v103, v101 row_shr:8 row_mask:0xf bank_mask:0xc
	s_nop 1
	v_mov_b32_dpp v102, v100 row_shl:8 row_mask:0xf bank_mask:0x3
	s_nop 1
	v_mov_b32_dpp v102, v100 row_shr:8 row_mask:0xf bank_mask:0xc
	s_waitcnt lgkmcnt(0)
	v_add_f32_e32 v0, v0, v92
	v_mul_f32_e32 v0, 0x3c800000, v0
	v_pk_add_f32 v[92:93], v[84:85], v[0:1] op_sel_hi:[1,0] neg_lo:[0,1] neg_hi:[0,1]
	v_pk_add_f32 v[84:85], v[96:97], v[0:1] op_sel_hi:[1,0] neg_lo:[0,1] neg_hi:[0,1]
	s_waitcnt lgkmcnt(0)
	v_pk_add_f32 v[100:101], v[100:101], v[102:103]
	v_pk_mul_f32 v[94:95], v[92:93], v[92:93]
	v_pk_fma_f32 v[100:101], v[100:101], s[6:7], v[104:105] op_sel_hi:[1,0,0]
	v_pk_mul_f32 v[96:97], v[84:85], v[84:85]
	v_mul_f32_e32 v0, 0x4b800000, v101
	v_cmp_gt_f32_e64 s[0:1], s29, v101
	v_cmp_gt_f32_e32 vcc, s29, v100
	s_nop 0
	v_cndmask_b32_e64 v0, v101, v0, s[0:1]
	v_rsq_f32_e32 v0, v0
	s_nop 0
	v_mul_f32_e32 v101, 0x45800000, v0
	v_cndmask_b32_e64 v103, v0, v101, s[0:1]
	v_mul_f32_e32 v0, 0x4b800000, v100
	v_cndmask_b32_e32 v0, v100, v0, vcc
	v_rsq_f32_e32 v0, v0
	v_mov_b32_e32 v101, v98
	v_mov_b32_e32 v98, v95
	v_mul_f32_e32 v86, v86, v103
	v_mul_f32_e32 v100, 0x45800000, v0
	v_cndmask_b32_e32 v102, v0, v100, vcc
	v_mov_b32_e32 v100, v94
	v_pk_add_f32 v[94:95], v[100:101], v[98:99]
	global_load_dword v100, v190, s[50:51]
	global_load_dword v101, v190, s[52:53]
	v_mov_b32_e32 v98, v97
	v_mov_b32_e32 v99, v111
	v_pk_add_f32 v[94:95], v[98:99], v[94:95]
	v_mov_b32_e32 v97, v110
	v_pk_add_f32 v[94:95], v[96:97], v[94:95]
	s_nop 1
	v_mov_b32_dpp v97, v95 quad_perm:[1,0,3,2] row_mask:0xf bank_mask:0xf
	s_nop 1
	v_mov_b32_dpp v96, v94 quad_perm:[1,0,3,2] row_mask:0xf bank_mask:0xf
	v_mul_f32_e32 v3, v3, v103
	v_mul_f32_e32 v2, v2, v103
	s_waitcnt lgkmcnt(0)
	v_pk_add_f32 v[94:95], v[94:95], v[96:97]
	s_nop 1
	v_mov_b32_dpp v97, v95 quad_perm:[2,3,0,1] row_mask:0xf bank_mask:0xf
	s_nop 1
	v_mov_b32_dpp v96, v94 quad_perm:[2,3,0,1] row_mask:0xf bank_mask:0xf
	s_waitcnt lgkmcnt(0)
	v_pk_add_f32 v[94:95], v[94:95], v[96:97]
	s_nop 1
	v_mov_b32_dpp v97, v95 row_shl:4 row_mask:0xf bank_mask:0x5
	s_nop 1
	v_mov_b32_dpp v97, v95 row_shr:4 row_mask:0xf bank_mask:0xa
	s_nop 1
	v_mov_b32_dpp v96, v94 row_shl:4 row_mask:0xf bank_mask:0x5
	s_nop 1
	v_mov_b32_dpp v96, v94 row_shr:4 row_mask:0xf bank_mask:0xa
	s_waitcnt lgkmcnt(0)
	v_pk_add_f32 v[94:95], v[94:95], v[96:97]
	s_nop 1
	v_mov_b32_dpp v97, v95 row_shl:8 row_mask:0xf bank_mask:0x3
	s_nop 1
	v_mov_b32_dpp v97, v95 row_shr:8 row_mask:0xf bank_mask:0xc
	s_nop 1
	v_mov_b32_dpp v96, v94 row_shl:8 row_mask:0xf bank_mask:0x3
	s_nop 1
	v_mov_b32_dpp v96, v94 row_shr:8 row_mask:0xf bank_mask:0xc
	s_waitcnt lgkmcnt(0)
	v_pk_add_f32 v[94:95], v[94:95], v[96:97]
	s_nop 0
	v_pk_fma_f32 v[94:95], v[94:95], s[6:7], v[104:105] op_sel_hi:[1,0,0]
	s_waitcnt vmcnt(0)
	v_fma_f32 v86, v86, v100, v101
	v_mul_f32_e32 v0, 0x4b800000, v95
	v_cmp_gt_f32_e64 s[0:1], s29, v95
	v_cmp_gt_f32_e32 vcc, s29, v94
	s_nop 0
	v_cndmask_b32_e64 v0, v95, v0, s[0:1]
	v_rsq_f32_e32 v0, v0
	s_nop 0
	v_mul_f32_e32 v95, 0x45800000, v0
	v_cndmask_b32_e64 v105, v0, v95, s[0:1]
	v_mul_f32_e32 v0, 0x4b800000, v94
	v_cndmask_b32_e32 v0, v94, v0, vcc
	v_rsq_f32_e32 v0, v0
	v_readlane_b32 s0, v254, 38
	v_readlane_b32 s1, v254, 39
	v_mul_f32_e32 v94, 0x45800000, v0
	v_cndmask_b32_e32 v104, v0, v94, vcc
	v_lshl_add_u32 v94, v144, 2, s5
	ds_read_b32 v106, v94
	v_or_b32_e32 v94, s4, v144
	v_lshlrev_b32_e32 v0, 1, v191
	v_ashrrev_i32_e32 v95, 31, v94
	v_lshl_add_u64 v[108:109], s[0:1], 0, v[0:1]
	s_waitcnt lgkmcnt(0)
	v_fmac_f32_e32 v86, v126, v106
	v_mul_f32_e32 v68, v68, v86
	v_lshlrev_b64 v[94:95], 11, v[94:95]
	v_cvt_pk_bf16_f32 v68, v68, v68
	v_lshl_add_u64 v[96:97], v[108:109], 0, v[94:95]
	v_lshl_add_u32 v86, v145, 2, s5
	global_store_short v[96:97], v68, off
	v_mul_f32_e32 v68, v88, v102
	ds_read_b32 v88, v86
	v_fma_f32 v68, v100, v68, v101
	s_waitcnt lgkmcnt(0)
	v_fmac_f32_e32 v68, v140, v88
	v_mul_f32_e32 v68, v69, v68
	v_cvt_pk_bf16_f32 v86, v68, v68
	v_or_b32_e32 v68, s4, v145
	v_ashrrev_i32_e32 v69, 31, v68
	v_lshlrev_b64 v[96:97], 11, v[68:69]
	v_lshl_add_u64 v[68:69], v[108:109], 0, v[96:97]
	global_store_short v[68:69], v86, off
	v_lshl_add_u32 v69, v146, 2, s5
	v_mul_f32_e32 v68, v90, v105
	ds_read_b32 v90, v69
	v_fma_f32 v68, v100, v68, v101
	s_waitcnt lgkmcnt(0)
	v_fmac_f32_e32 v68, v141, v90
	v_mul_f32_e32 v68, v70, v68
	v_cvt_pk_bf16_f32 v70, v68, v68
	v_or_b32_e32 v68, s4, v146
	v_ashrrev_i32_e32 v69, 31, v68
	v_lshlrev_b64 v[98:99], 11, v[68:69]
	v_lshl_add_u64 v[68:69], v[108:109], 0, v[98:99]
	global_store_short v[68:69], v70, off
	v_mul_f32_e32 v68, v92, v104
	v_fmac_f32_e32 v101, v100, v68
	v_lshl_add_u32 v68, v147, 2, s5
	ds_read_b32 v92, v68
	s_waitcnt lgkmcnt(0)
	v_fmac_f32_e32 v101, v129, v92
	v_mul_f32_e32 v68, v71, v101
	v_cvt_pk_bf16_f32 v70, v68, v68
	v_or_b32_e32 v68, s4, v147
	v_ashrrev_i32_e32 v69, 31, v68
	v_lshlrev_b64 v[100:101], 11, v[68:69]
	v_lshl_add_u64 v[68:69], v[108:109], 0, v[100:101]
	global_store_short v[68:69], v70, off
	global_load_dword v107, v190, s[50:51] offset:64
	global_load_dword v108, v190, s[52:53] offset:64
	v_mul_f32_e32 v68, v87, v103
	v_lshl_add_u64 v[86:87], s[0:1], 0, v[96:97]
	s_waitcnt vmcnt(0)
	v_fma_f32 v68, v68, v107, v108
	v_fmac_f32_e32 v68, v128, v106
	v_mul_f32_e32 v64, v64, v68
	v_lshl_add_u64 v[68:69], s[0:1], 0, v[94:95]
	v_or_b32_e32 v94, 32, v0
	v_mov_b32_e32 v95, v1
	v_cvt_pk_bf16_f32 v64, v64, v64
	v_lshl_add_u64 v[70:71], v[68:69], 0, v[94:95]
	global_store_short v[70:71], v64, off
	v_mul_f32_e32 v64, v89, v102
	v_fma_f32 v64, v64, v107, v108
	v_fmac_f32_e32 v64, v138, v88
	v_mul_f32_e32 v64, v65, v64
	v_cvt_pk_bf16_f32 v70, v64, v64
	v_lshl_add_u64 v[64:65], v[86:87], 0, v[94:95]
	global_store_short v[64:65], v70, off
	v_mul_f32_e32 v64, v91, v105
	v_fma_f32 v64, v64, v107, v108
	v_fmac_f32_e32 v64, v139, v90
	v_mul_f32_e32 v64, v66, v64
	v_lshl_add_u64 v[70:71], s[0:1], 0, v[98:99]
	v_cvt_pk_bf16_f32 v66, v64, v64
	v_lshl_add_u64 v[64:65], v[70:71], 0, v[94:95]
	global_store_short v[64:65], v66, off
	v_mul_f32_e32 v64, v93, v104
	v_fmac_f32_e32 v108, v64, v107
	v_fmac_f32_e32 v108, v131, v92
	v_mul_f32_e32 v64, v67, v108
	v_cvt_pk_bf16_f32 v89, v64, v64
	v_lshl_add_u64 v[64:65], s[0:1], 0, v[100:101]
	v_lshl_add_u64 v[66:67], v[64:65], 0, v[94:95]
	global_store_short v[66:67], v89, off
	global_load_dword v89, v190, s[50:51] offset:128
	s_nop 0
	global_load_dword v91, v190, s[52:53] offset:128
	v_or_b32_e32 v66, 64, v0
	v_mov_b32_e32 v67, v1
	v_lshl_add_u64 v[94:95], v[68:69], 0, v[66:67]
	v_or_b32_e32 v0, 0x60, v0
	s_waitcnt vmcnt(0)
	v_fma_f32 v3, v3, v89, v91
	v_fmac_f32_e32 v3, v130, v106
	v_mul_f32_e32 v3, v72, v3
	v_cvt_pk_bf16_f32 v3, v3, v3
	global_store_short v[94:95], v3, off
	v_mul_f32_e32 v3, v81, v102
	v_fma_f32 v3, v3, v89, v91
	v_fmac_f32_e32 v3, v136, v88
	v_mul_f32_e32 v3, v73, v3
	v_cvt_pk_bf16_f32 v3, v3, v3
	v_lshl_add_u64 v[72:73], v[86:87], 0, v[66:67]
	global_store_short v[72:73], v3, off
	v_mul_f32_e32 v3, v83, v105
	v_fma_f32 v3, v3, v89, v91
	v_fmac_f32_e32 v3, v137, v90
	v_mul_f32_e32 v3, v74, v3
	v_cvt_pk_bf16_f32 v3, v3, v3
	v_lshl_add_u64 v[72:73], v[70:71], 0, v[66:67]
	global_store_short v[72:73], v3, off
	v_mul_f32_e32 v3, v85, v104
	v_fmac_f32_e32 v91, v3, v89
	v_fmac_f32_e32 v91, v133, v92
	v_mul_f32_e32 v3, v75, v91
	v_lshl_add_u64 v[66:67], v[64:65], 0, v[66:67]
	v_cvt_pk_bf16_f32 v3, v3, v3
	global_store_short v[66:67], v3, off
	global_load_dword v66, v190, s[50:51] offset:192
	s_nop 0
	global_load_dword v67, v190, s[52:53] offset:192
	s_waitcnt vmcnt(0)
	v_fma_f32 v2, v2, v66, v67
	v_fmac_f32_e32 v2, v132, v106
	v_mul_f32_e32 v2, v76, v2
	v_cvt_pk_bf16_f32 v72, v2, v2
	v_lshl_add_u64 v[2:3], v[68:69], 0, v[0:1]
	global_store_short v[2:3], v72, off
	v_mul_f32_e32 v2, v80, v102
	v_fma_f32 v2, v2, v66, v67
	v_fmac_f32_e32 v2, v134, v88
	v_mul_f32_e32 v2, v77, v2
	v_cvt_pk_bf16_f32 v68, v2, v2
	v_lshl_add_u64 v[2:3], v[86:87], 0, v[0:1]
	global_store_short v[2:3], v68, off
	v_mul_f32_e32 v2, v82, v105
	v_fma_f32 v2, v2, v66, v67
	v_fmac_f32_e32 v2, v135, v90
	v_mul_f32_e32 v2, v78, v2
	v_cvt_pk_bf16_f32 v68, v2, v2
	v_lshl_add_u64 v[2:3], v[70:71], 0, v[0:1]
	global_store_short v[2:3], v68, off
	v_mul_f32_e32 v2, v84, v104
	v_fmac_f32_e32 v67, v2, v66
	v_fmac_f32_e32 v67, v127, v92
	v_mul_f32_e32 v2, v79, v67
	v_cvt_pk_bf16_f32 v66, v2, v2
	v_lshl_add_u64 v[2:3], v[64:65], 0, v[0:1]
	global_store_short v[2:3], v66, off
	s_branch .LBB0_819

.LBB0_1106:
	ds_read2st64_b32 v[28:29], v120 offset1:1
	v_and_b32_e32 v0, 64, v179
	v_add_u32_e32 v0, 64, v0
	v_xor_b32_e32 v26, 1, v179
	v_cmp_lt_i32_e32 vcc, v26, v0
	s_waitcnt lgkmcnt(0)
	v_pk_mul_f32 v[48:49], v[28:29], v[28:29]
	s_lshl_b32 s10, s4, 1
	v_cndmask_b32_e32 v26, v179, v26, vcc
	v_lshlrev_b32_e32 v47, 2, v26
	v_add_f32_e32 v48, v48, v49
	s_nop 1
	v_mov_b32_dpp v49, v48 quad_perm:[1,0,3,2] row_mask:0xf bank_mask:0xf
	v_xor_b32_e32 v26, 2, v179
	v_cmp_lt_i32_e32 vcc, v26, v0
	v_lshlrev_b64 v[42:43], 11, v[42:43]
	s_waitcnt lgkmcnt(0)
	v_add_f32_e32 v48, v48, v49
	v_cndmask_b32_e32 v26, v179, v26, vcc
	v_lshlrev_b32_e32 v46, 2, v26
	s_nop 1
	v_mov_b32_dpp v49, v48 quad_perm:[2,3,0,1] row_mask:0xf bank_mask:0xf
	v_xor_b32_e32 v26, 4, v179
	v_cmp_lt_i32_e32 vcc, v26, v0
	s_waitcnt lgkmcnt(0)
	v_add_f32_e32 v48, v48, v49
	v_cndmask_b32_e32 v26, v179, v26, vcc
	v_lshlrev_b32_e32 v45, 2, v26
	s_nop 1
	v_mov_b32_dpp v49, v48 row_shl:4 row_mask:0xf bank_mask:0x5
	s_nop 1
	v_mov_b32_dpp v49, v48 row_shr:4 row_mask:0xf bank_mask:0xa
	v_xor_b32_e32 v26, 8, v179
	v_cmp_lt_i32_e32 vcc, v26, v0
	s_waitcnt lgkmcnt(0)
	v_add_f32_e32 v48, v48, v49
	v_cndmask_b32_e32 v26, v179, v26, vcc
	v_lshlrev_b32_e32 v44, 2, v26
	s_nop 1
	v_mov_b32_dpp v49, v48 row_shl:8 row_mask:0xf bank_mask:0x3
	s_nop 1
	v_mov_b32_dpp v49, v48 row_shr:8 row_mask:0xf bank_mask:0xc
	v_xor_b32_e32 v26, 16, v179
	v_cmp_lt_i32_e32 vcc, v26, v0
	s_waitcnt lgkmcnt(0)
	v_add_f32_e32 v48, v48, v49
	v_cndmask_b32_e32 v26, v179, v26, vcc
	v_lshlrev_b32_e32 v41, 2, v26
	v_mov_b32_e32 v49, v48
	s_nop 1
	v_permlane16_swap_b32 v49, v48
	v_xor_b32_e32 v26, 32, v179
	v_cmp_lt_i32_e32 vcc, v26, v0
	s_waitcnt lgkmcnt(0)
	v_add_f32_e32 v48, v48, v49
	v_cndmask_b32_e32 v0, v179, v26, vcc
	v_lshlrev_b32_e32 v0, 2, v0
	v_mov_b32_e32 v49, v48
	s_nop 1
	v_permlane32_swap_b32 v49, v48
	v_lshl_add_u64 v[26:27], v[36:37], 0, s[10:11]
	v_lshl_add_u64 v[42:43], v[26:27], 0, v[42:43]
	s_waitcnt lgkmcnt(0)
	v_add_f32_e32 v48, v48, v49
	v_fmamk_f32 v48, v48, 0x3c000000, v184
	v_cmp_gt_f32_e32 vcc, s29, v48
	v_mul_f32_e32 v49, 0x4b800000, v48
	s_nop 0
	v_cndmask_b32_e32 v48, v48, v49, vcc
	v_rsq_f32_e32 v48, v48
	s_nop 0
	v_mul_f32_e32 v49, 0x45800000, v48
	v_cndmask_b32_e32 v48, v48, v49, vcc
	s_waitcnt vmcnt(15)
	v_lshlrev_b32_e32 v49, 16, v150
	v_mul_f32_e32 v50, 0xbfb8aa3b, v49
	v_exp_f32_e32 v50, v50
	v_mul_f32_e32 v28, v28, v48
	v_mul_f32_e32 v28, v137, v28
	v_add_f32_e32 v50, 1.0, v50
	v_rcp_f32_e32 v50, v50
	s_nop 0
	v_mul_f32_e32 v49, v50, v49
	v_mul_f32_e32 v28, v49, v28
	v_cvt_pk_bf16_f32 v28, v28, v28
	global_store_short v[42:43], v28, off
	v_mul_f32_e32 v28, v29, v48
	s_waitcnt vmcnt(15)
	v_lshlrev_b32_e32 v29, 16, v151
	v_mul_f32_e32 v48, 0xbfb8aa3b, v29
	v_exp_f32_e32 v48, v48
	v_mul_f32_e32 v28, v159, v28
	v_add_f32_e32 v48, 1.0, v48
	v_rcp_f32_e32 v48, v48
	s_nop 0
	v_mul_f32_e32 v29, v48, v29
	v_mul_f32_e32 v28, v29, v28
	v_cvt_pk_bf16_f32 v28, v28, v28
	global_store_short v[42:43], v28, off offset:128
	ds_read2st64_b32 v[42:43], v122 offset1:1
	v_add_u32_e32 v28, s93, v121
	s_waitcnt lgkmcnt(0)
	v_pk_mul_f32 v[48:49], v[42:43], v[42:43]
	v_add_f32_e32 v29, v48, v49
	s_nop 1
	v_mov_b32_dpp v48, v29 quad_perm:[1,0,3,2] row_mask:0xf bank_mask:0xf
	s_waitcnt lgkmcnt(0)
	v_add_f32_e32 v29, v29, v48
	s_nop 1
	v_mov_b32_dpp v48, v29 quad_perm:[2,3,0,1] row_mask:0xf bank_mask:0xf
	s_waitcnt lgkmcnt(0)
	v_add_f32_e32 v29, v29, v48
	s_nop 1
	v_mov_b32_dpp v48, v29 row_shl:4 row_mask:0xf bank_mask:0x5
	s_nop 1
	v_mov_b32_dpp v48, v29 row_shr:4 row_mask:0xf bank_mask:0xa
	s_waitcnt lgkmcnt(0)
	v_add_f32_e32 v29, v29, v48
	s_nop 1
	v_mov_b32_dpp v48, v29 row_shl:8 row_mask:0xf bank_mask:0x3
	s_nop 1
	v_mov_b32_dpp v48, v29 row_shr:8 row_mask:0xf bank_mask:0xc
	s_waitcnt lgkmcnt(0)
	v_add_f32_e32 v29, v29, v48
	v_mov_b32_e32 v48, v29
	s_nop 1
	v_permlane16_swap_b32 v48, v29
	s_waitcnt lgkmcnt(0)
	v_add_f32_e32 v29, v29, v48
	v_mov_b32_e32 v48, v29
	s_nop 1
	v_permlane32_swap_b32 v48, v29
	s_waitcnt lgkmcnt(0)
	v_add_f32_e32 v29, v29, v48
	v_fmamk_f32 v29, v29, 0x3c000000, v184
	v_cmp_gt_f32_e32 vcc, s29, v29
	v_mul_f32_e32 v48, 0x4b800000, v29
	s_nop 0
	v_cndmask_b32_e32 v29, v29, v48, vcc
	v_rsq_f32_e32 v29, v29
	s_nop 0
	v_mul_f32_e32 v48, 0x45800000, v29
	v_cndmask_b32_e32 v48, v29, v48, vcc
	v_mul_f32_e32 v29, v42, v48
	s_waitcnt vmcnt(15)
	v_lshlrev_b32_e32 v42, 16, v152
	v_mul_f32_e32 v49, 0xbfb8aa3b, v42
	v_exp_f32_e32 v49, v49
	v_mul_f32_e32 v29, v137, v29
	v_add_f32_e32 v49, 1.0, v49
	v_rcp_f32_e32 v49, v49
	s_nop 0
	v_mul_f32_e32 v42, v49, v42
	v_mul_f32_e32 v29, v42, v29
	v_cvt_pk_bf16_f32 v42, v29, v29
	v_ashrrev_i32_e32 v29, 31, v28
	v_lshlrev_b64 v[28:29], 11, v[28:29]
	v_lshl_add_u64 v[28:29], v[26:27], 0, v[28:29]
	global_store_short v[28:29], v42, off
	v_mul_f32_e32 v42, v43, v48
	s_waitcnt vmcnt(15)
	v_lshlrev_b32_e32 v43, 16, v153
	v_mul_f32_e32 v48, 0xbfb8aa3b, v43
	v_exp_f32_e32 v48, v48
	v_mul_f32_e32 v42, v159, v42
	v_add_f32_e32 v48, 1.0, v48
	v_rcp_f32_e32 v48, v48
	s_nop 0
	v_mul_f32_e32 v43, v48, v43
	v_mul_f32_e32 v42, v43, v42
	v_cvt_pk_bf16_f32 v42, v42, v42
	global_store_short v[28:29], v42, off offset:128
	ds_read2st64_b32 v[42:43], v126 offset1:1
	v_add_u32_e32 v28, s93, v123
	s_waitcnt lgkmcnt(0)
	v_pk_mul_f32 v[48:49], v[42:43], v[42:43]
	v_add_f32_e32 v29, v48, v49
	s_nop 1
	v_mov_b32_dpp v48, v29 quad_perm:[1,0,3,2] row_mask:0xf bank_mask:0xf
	s_waitcnt lgkmcnt(0)
	v_add_f32_e32 v29, v29, v48
	s_nop 1
	v_mov_b32_dpp v48, v29 quad_perm:[2,3,0,1] row_mask:0xf bank_mask:0xf
	s_waitcnt lgkmcnt(0)
	v_add_f32_e32 v29, v29, v48
	s_nop 1
	v_mov_b32_dpp v48, v29 row_shl:4 row_mask:0xf bank_mask:0x5
	s_nop 1
	v_mov_b32_dpp v48, v29 row_shr:4 row_mask:0xf bank_mask:0xa
	s_waitcnt lgkmcnt(0)
	v_add_f32_e32 v29, v29, v48
	s_nop 1
	v_mov_b32_dpp v48, v29 row_shl:8 row_mask:0xf bank_mask:0x3
	s_nop 1
	v_mov_b32_dpp v48, v29 row_shr:8 row_mask:0xf bank_mask:0xc
	s_waitcnt lgkmcnt(0)
	v_add_f32_e32 v29, v29, v48
	v_mov_b32_e32 v48, v29
	s_nop 1
	v_permlane16_swap_b32 v48, v29
	s_waitcnt lgkmcnt(0)
	v_add_f32_e32 v29, v29, v48
	v_mov_b32_e32 v48, v29
	s_nop 1
	v_permlane32_swap_b32 v48, v29
	s_waitcnt lgkmcnt(0)
	v_add_f32_e32 v29, v29, v48
	v_fmamk_f32 v29, v29, 0x3c000000, v184
	v_cmp_gt_f32_e32 vcc, s29, v29
	v_mul_f32_e32 v48, 0x4b800000, v29
	s_nop 0
	v_cndmask_b32_e32 v29, v29, v48, vcc
	v_rsq_f32_e32 v29, v29
	s_nop 0
	v_mul_f32_e32 v48, 0x45800000, v29
	v_cndmask_b32_e32 v48, v29, v48, vcc
	v_mul_f32_e32 v29, v42, v48
	s_waitcnt vmcnt(15)
	v_lshlrev_b32_e32 v42, 16, v154
	v_mul_f32_e32 v49, 0xbfb8aa3b, v42
	v_exp_f32_e32 v49, v49
	v_mul_f32_e32 v29, v137, v29
	v_add_f32_e32 v49, 1.0, v49
	v_rcp_f32_e32 v49, v49
	s_nop 0
	v_mul_f32_e32 v42, v49, v42
	v_mul_f32_e32 v29, v42, v29
	v_cvt_pk_bf16_f32 v42, v29, v29
	v_ashrrev_i32_e32 v29, 31, v28
	v_lshlrev_b64 v[28:29], 11, v[28:29]
	v_lshl_add_u64 v[28:29], v[26:27], 0, v[28:29]
	global_store_short v[28:29], v42, off
	v_mul_f32_e32 v42, v43, v48
	s_waitcnt vmcnt(15)
	v_lshlrev_b32_e32 v43, 16, v155
	v_mul_f32_e32 v48, 0xbfb8aa3b, v43
	v_exp_f32_e32 v48, v48
	v_mul_f32_e32 v42, v159, v42
	v_add_f32_e32 v48, 1.0, v48
	v_rcp_f32_e32 v48, v48
	s_nop 0
	v_mul_f32_e32 v43, v48, v43
	v_mul_f32_e32 v42, v43, v42
	v_cvt_pk_bf16_f32 v42, v42, v42
	global_store_short v[28:29], v42, off offset:128
	ds_read2st64_b32 v[42:43], v128 offset1:1
	v_add_u32_e32 v28, s93, v127
	s_waitcnt lgkmcnt(0)
	v_pk_mul_f32 v[48:49], v[42:43], v[42:43]
	v_add_f32_e32 v29, v48, v49
	s_nop 1
	v_mov_b32_dpp v48, v29 quad_perm:[1,0,3,2] row_mask:0xf bank_mask:0xf
	s_waitcnt lgkmcnt(0)
	v_add_f32_e32 v29, v29, v48
	s_nop 1
	v_mov_b32_dpp v48, v29 quad_perm:[2,3,0,1] row_mask:0xf bank_mask:0xf
	s_waitcnt lgkmcnt(0)
	v_add_f32_e32 v29, v29, v48
	s_nop 1
	v_mov_b32_dpp v48, v29 row_shl:4 row_mask:0xf bank_mask:0x5
	s_nop 1
	v_mov_b32_dpp v48, v29 row_shr:4 row_mask:0xf bank_mask:0xa
	s_waitcnt lgkmcnt(0)
	v_add_f32_e32 v29, v29, v48
	s_nop 1
	v_mov_b32_dpp v48, v29 row_shl:8 row_mask:0xf bank_mask:0x3
	s_nop 1
	v_mov_b32_dpp v48, v29 row_shr:8 row_mask:0xf bank_mask:0xc
	s_waitcnt lgkmcnt(0)
	v_add_f32_e32 v29, v29, v48
	v_mov_b32_e32 v48, v29
	s_nop 1
	v_permlane16_swap_b32 v48, v29
	s_waitcnt lgkmcnt(0)
	v_add_f32_e32 v29, v29, v48
	v_mov_b32_e32 v48, v29
	s_nop 1
	v_permlane32_swap_b32 v48, v29
	s_waitcnt lgkmcnt(0)
	v_add_f32_e32 v29, v29, v48
	v_fmamk_f32 v29, v29, 0x3c000000, v184
	v_cmp_gt_f32_e32 vcc, s29, v29
	v_mul_f32_e32 v48, 0x4b800000, v29
	s_nop 0
	v_cndmask_b32_e32 v29, v29, v48, vcc
	v_rsq_f32_e32 v29, v29
	s_nop 0
	v_mul_f32_e32 v48, 0x45800000, v29
	v_cndmask_b32_e32 v48, v29, v48, vcc
	v_mul_f32_e32 v29, v42, v48
	s_waitcnt vmcnt(15)
	v_lshlrev_b32_e32 v42, 16, v156
	v_mul_f32_e32 v49, 0xbfb8aa3b, v42
	v_exp_f32_e32 v49, v49
	v_mul_f32_e32 v29, v137, v29
	v_add_f32_e32 v49, 1.0, v49
	v_rcp_f32_e32 v49, v49
	s_nop 0
	v_mul_f32_e32 v42, v49, v42
	v_mul_f32_e32 v29, v42, v29
	v_cvt_pk_bf16_f32 v42, v29, v29
	v_ashrrev_i32_e32 v29, 31, v28
	v_lshlrev_b64 v[28:29], 11, v[28:29]
	v_lshl_add_u64 v[28:29], v[26:27], 0, v[28:29]
	global_store_short v[28:29], v42, off
	v_mul_f32_e32 v42, v43, v48
	s_waitcnt vmcnt(15)
	v_lshlrev_b32_e32 v43, 16, v157
	v_mul_f32_e32 v48, 0xbfb8aa3b, v43
	v_exp_f32_e32 v48, v48
	v_mul_f32_e32 v42, v159, v42
	v_add_f32_e32 v48, 1.0, v48
	v_rcp_f32_e32 v48, v48
	s_nop 0
	v_mul_f32_e32 v43, v48, v43
	v_mul_f32_e32 v42, v43, v42
	v_cvt_pk_bf16_f32 v42, v42, v42
	global_store_short v[28:29], v42, off offset:128
	ds_read2st64_b32 v[42:43], v130 offset1:1
	v_add_u32_e32 v28, s93, v129
	s_waitcnt lgkmcnt(0)
	v_pk_mul_f32 v[48:49], v[42:43], v[42:43]
	v_add_f32_e32 v29, v48, v49
	s_nop 1
	v_mov_b32_dpp v48, v29 quad_perm:[1,0,3,2] row_mask:0xf bank_mask:0xf
	s_waitcnt lgkmcnt(0)
	v_add_f32_e32 v29, v29, v48
	s_nop 1
	v_mov_b32_dpp v48, v29 quad_perm:[2,3,0,1] row_mask:0xf bank_mask:0xf
	s_waitcnt lgkmcnt(0)
	v_add_f32_e32 v29, v29, v48
	s_nop 1
	v_mov_b32_dpp v48, v29 row_shl:4 row_mask:0xf bank_mask:0x5
	s_nop 1
	v_mov_b32_dpp v48, v29 row_shr:4 row_mask:0xf bank_mask:0xa
	s_waitcnt lgkmcnt(0)
	v_add_f32_e32 v29, v29, v48
	s_nop 1
	v_mov_b32_dpp v48, v29 row_shl:8 row_mask:0xf bank_mask:0x3
	s_nop 1
	v_mov_b32_dpp v48, v29 row_shr:8 row_mask:0xf bank_mask:0xc
	s_waitcnt lgkmcnt(0)
	v_add_f32_e32 v29, v29, v48
	v_mov_b32_e32 v48, v29
	s_nop 1
	v_permlane16_swap_b32 v48, v29
	s_waitcnt lgkmcnt(0)
	v_add_f32_e32 v29, v29, v48
	v_mov_b32_e32 v48, v29
	s_nop 1
	v_permlane32_swap_b32 v48, v29
	s_waitcnt lgkmcnt(0)
	v_add_f32_e32 v29, v29, v48
	v_fmamk_f32 v29, v29, 0x3c000000, v184
	v_cmp_gt_f32_e32 vcc, s29, v29
	v_mul_f32_e32 v48, 0x4b800000, v29
	s_nop 0
	v_cndmask_b32_e32 v29, v29, v48, vcc
	v_rsq_f32_e32 v29, v29
	s_nop 0
	v_mul_f32_e32 v48, 0x45800000, v29
	v_cndmask_b32_e32 v48, v29, v48, vcc
	v_mul_f32_e32 v29, v42, v48
	s_waitcnt vmcnt(15)
	v_lshlrev_b32_e32 v42, 16, v158
	v_mul_f32_e32 v49, 0xbfb8aa3b, v42
	v_exp_f32_e32 v49, v49
	v_mul_f32_e32 v29, v137, v29
	v_add_f32_e32 v49, 1.0, v49
	v_rcp_f32_e32 v49, v49
	s_nop 0
	v_mul_f32_e32 v42, v49, v42
	v_mul_f32_e32 v29, v42, v29
	v_cvt_pk_bf16_f32 v42, v29, v29
	v_ashrrev_i32_e32 v29, 31, v28
	v_lshlrev_b64 v[28:29], 11, v[28:29]
	v_lshl_add_u64 v[28:29], v[26:27], 0, v[28:29]
	global_store_short v[28:29], v42, off
	v_mul_f32_e32 v42, v43, v48
	s_waitcnt vmcnt(15)
	v_lshlrev_b32_e32 v43, 16, v164
	v_mul_f32_e32 v48, 0xbfb8aa3b, v43
	v_exp_f32_e32 v48, v48
	v_mul_f32_e32 v42, v159, v42
	v_add_f32_e32 v48, 1.0, v48
	v_rcp_f32_e32 v48, v48
	s_nop 0
	v_mul_f32_e32 v43, v48, v43
	v_mul_f32_e32 v42, v43, v42
	v_cvt_pk_bf16_f32 v42, v42, v42
	global_store_short v[28:29], v42, off offset:128
	ds_read2st64_b32 v[42:43], v132 offset1:1
	v_add_u32_e32 v28, s93, v131
	s_waitcnt lgkmcnt(0)
	v_pk_mul_f32 v[48:49], v[42:43], v[42:43]
	v_add_f32_e32 v29, v48, v49
	s_nop 1
	v_mov_b32_dpp v48, v29 quad_perm:[1,0,3,2] row_mask:0xf bank_mask:0xf
	s_waitcnt lgkmcnt(0)
	v_add_f32_e32 v29, v29, v48
	s_nop 1
	v_mov_b32_dpp v48, v29 quad_perm:[2,3,0,1] row_mask:0xf bank_mask:0xf
	s_waitcnt lgkmcnt(0)
	v_add_f32_e32 v29, v29, v48
	s_nop 1
	v_mov_b32_dpp v48, v29 row_shl:4 row_mask:0xf bank_mask:0x5
	s_nop 1
	v_mov_b32_dpp v48, v29 row_shr:4 row_mask:0xf bank_mask:0xa
	s_waitcnt lgkmcnt(0)
	v_add_f32_e32 v29, v29, v48
	s_nop 1
	v_mov_b32_dpp v48, v29 row_shl:8 row_mask:0xf bank_mask:0x3
	s_nop 1
	v_mov_b32_dpp v48, v29 row_shr:8 row_mask:0xf bank_mask:0xc
	s_waitcnt lgkmcnt(0)
	v_add_f32_e32 v29, v29, v48
	v_mov_b32_e32 v48, v29
	s_nop 1
	v_permlane16_swap_b32 v48, v29
	s_waitcnt lgkmcnt(0)
	v_add_f32_e32 v29, v29, v48
	v_mov_b32_e32 v48, v29
	s_nop 1
	v_permlane32_swap_b32 v48, v29
	s_waitcnt lgkmcnt(0)
	v_add_f32_e32 v29, v29, v48
	v_fmamk_f32 v29, v29, 0x3c000000, v184
	v_cmp_gt_f32_e32 vcc, s29, v29
	v_mul_f32_e32 v48, 0x4b800000, v29
	s_nop 0
	v_cndmask_b32_e32 v29, v29, v48, vcc
	v_rsq_f32_e32 v29, v29
	s_nop 0
	v_mul_f32_e32 v48, 0x45800000, v29
	v_cndmask_b32_e32 v48, v29, v48, vcc
	v_mul_f32_e32 v29, v42, v48
	s_waitcnt vmcnt(15)
	v_lshlrev_b32_e32 v42, 16, v165
	v_mul_f32_e32 v49, 0xbfb8aa3b, v42
	v_exp_f32_e32 v49, v49
	v_mul_f32_e32 v29, v137, v29
	v_add_f32_e32 v49, 1.0, v49
	v_rcp_f32_e32 v49, v49
	s_nop 0
	v_mul_f32_e32 v42, v49, v42
	v_mul_f32_e32 v29, v42, v29
	v_cvt_pk_bf16_f32 v42, v29, v29
	v_ashrrev_i32_e32 v29, 31, v28
	v_lshlrev_b64 v[28:29], 11, v[28:29]
	v_lshl_add_u64 v[28:29], v[26:27], 0, v[28:29]
	global_store_short v[28:29], v42, off
	v_mul_f32_e32 v42, v43, v48
	s_waitcnt vmcnt(15)
	v_lshlrev_b32_e32 v43, 16, v166
	v_mul_f32_e32 v48, 0xbfb8aa3b, v43
	v_exp_f32_e32 v48, v48
	v_mul_f32_e32 v42, v159, v42
	v_add_f32_e32 v48, 1.0, v48
	v_rcp_f32_e32 v48, v48
	s_nop 0
	v_mul_f32_e32 v43, v48, v43
	v_mul_f32_e32 v42, v43, v42
	v_cvt_pk_bf16_f32 v42, v42, v42
	global_store_short v[28:29], v42, off offset:128
	ds_read2st64_b32 v[42:43], v134 offset1:1
	v_add_u32_e32 v28, s93, v133
	s_waitcnt lgkmcnt(0)
	v_pk_mul_f32 v[48:49], v[42:43], v[42:43]
	v_add_f32_e32 v29, v48, v49
	s_nop 1
	v_mov_b32_dpp v48, v29 quad_perm:[1,0,3,2] row_mask:0xf bank_mask:0xf
	s_waitcnt lgkmcnt(0)
	v_add_f32_e32 v29, v29, v48
	s_nop 1
	v_mov_b32_dpp v48, v29 quad_perm:[2,3,0,1] row_mask:0xf bank_mask:0xf
	s_waitcnt lgkmcnt(0)
	v_add_f32_e32 v29, v29, v48
	s_nop 1
	v_mov_b32_dpp v48, v29 row_shl:4 row_mask:0xf bank_mask:0x5
	s_nop 1
	v_mov_b32_dpp v48, v29 row_shr:4 row_mask:0xf bank_mask:0xa
	s_waitcnt lgkmcnt(0)
	v_add_f32_e32 v29, v29, v48
	s_nop 1
	v_mov_b32_dpp v48, v29 row_shl:8 row_mask:0xf bank_mask:0x3
	s_nop 1
	v_mov_b32_dpp v48, v29 row_shr:8 row_mask:0xf bank_mask:0xc
	s_waitcnt lgkmcnt(0)
	v_add_f32_e32 v29, v29, v48
	v_mov_b32_e32 v48, v29
	s_nop 1
	v_permlane16_swap_b32 v48, v29
	s_waitcnt lgkmcnt(0)
	v_add_f32_e32 v29, v29, v48
	v_mov_b32_e32 v48, v29
	s_nop 1
	v_permlane32_swap_b32 v48, v29
	s_waitcnt lgkmcnt(0)
	v_add_f32_e32 v29, v29, v48
	v_fmamk_f32 v29, v29, 0x3c000000, v184
	v_cmp_gt_f32_e32 vcc, s29, v29
	v_mul_f32_e32 v48, 0x4b800000, v29
	s_nop 0
	v_cndmask_b32_e32 v29, v29, v48, vcc
	v_rsq_f32_e32 v29, v29
	s_nop 0
	v_mul_f32_e32 v48, 0x45800000, v29
	v_cndmask_b32_e32 v48, v29, v48, vcc
	v_mul_f32_e32 v29, v42, v48
	s_waitcnt vmcnt(15)
	v_lshlrev_b32_e32 v42, 16, v167
	v_mul_f32_e32 v49, 0xbfb8aa3b, v42
	v_exp_f32_e32 v49, v49
	v_mul_f32_e32 v29, v137, v29
	v_add_f32_e32 v49, 1.0, v49
	v_rcp_f32_e32 v49, v49
	s_nop 0
	v_mul_f32_e32 v42, v49, v42
	v_mul_f32_e32 v29, v42, v29
	v_cvt_pk_bf16_f32 v42, v29, v29
	v_ashrrev_i32_e32 v29, 31, v28
	v_lshlrev_b64 v[28:29], 11, v[28:29]
	v_lshl_add_u64 v[28:29], v[26:27], 0, v[28:29]
	global_store_short v[28:29], v42, off
	v_mul_f32_e32 v42, v43, v48
	s_waitcnt vmcnt(15)
	v_lshlrev_b32_e32 v43, 16, v168
	v_mul_f32_e32 v48, 0xbfb8aa3b, v43
	v_exp_f32_e32 v48, v48
	v_mul_f32_e32 v42, v159, v42
	v_add_f32_e32 v48, 1.0, v48
	v_rcp_f32_e32 v48, v48
	s_nop 0
	v_mul_f32_e32 v43, v48, v43
	v_mul_f32_e32 v42, v43, v42
	v_cvt_pk_bf16_f32 v42, v42, v42
	global_store_short v[28:29], v42, off offset:128
	ds_read2st64_b32 v[42:43], v136 offset1:1
	v_add_u32_e32 v28, s93, v135
	s_waitcnt lgkmcnt(0)
	v_pk_mul_f32 v[48:49], v[42:43], v[42:43]
	v_add_f32_e32 v29, v48, v49
	s_nop 1
	v_mov_b32_dpp v47, v29 quad_perm:[1,0,3,2] row_mask:0xf bank_mask:0xf
	s_waitcnt lgkmcnt(0)
	v_add_f32_e32 v29, v29, v47
	s_nop 1
	v_mov_b32_dpp v46, v29 quad_perm:[2,3,0,1] row_mask:0xf bank_mask:0xf
	s_waitcnt lgkmcnt(0)
	v_add_f32_e32 v29, v29, v46
	s_nop 1
	v_mov_b32_dpp v45, v29 row_shl:4 row_mask:0xf bank_mask:0x5
	s_nop 1
	v_mov_b32_dpp v45, v29 row_shr:4 row_mask:0xf bank_mask:0xa
	s_waitcnt lgkmcnt(0)
	v_add_f32_e32 v29, v29, v45
	s_nop 1
	v_mov_b32_dpp v44, v29 row_shl:8 row_mask:0xf bank_mask:0x3
	s_nop 1
	v_mov_b32_dpp v44, v29 row_shr:8 row_mask:0xf bank_mask:0xc
	s_waitcnt lgkmcnt(0)
	v_add_f32_e32 v29, v29, v44
	v_mov_b32_e32 v41, v29
	s_nop 1
	v_permlane16_swap_b32 v41, v29
	s_waitcnt lgkmcnt(0)
	v_add_f32_e32 v29, v29, v41
	v_mov_b32_e32 v0, v29
	s_nop 1
	v_permlane32_swap_b32 v0, v29
	s_waitcnt vmcnt(15)
	v_lshlrev_b32_e32 v41, 16, v169
	s_waitcnt lgkmcnt(0)
	v_add_f32_e32 v0, v29, v0
	v_fmamk_f32 v0, v0, 0x3c000000, v184
	v_cmp_gt_f32_e32 vcc, s29, v0
	v_mul_f32_e32 v29, 0x4b800000, v0
	s_nop 0
	v_cndmask_b32_e32 v0, v0, v29, vcc
	v_rsq_f32_e32 v0, v0
	s_nop 0
	v_mul_f32_e32 v29, 0x45800000, v0
	v_cndmask_b32_e32 v0, v0, v29, vcc
	v_mul_f32_e32 v29, v42, v0
	v_mul_f32_e32 v42, 0xbfb8aa3b, v41
	v_exp_f32_e32 v42, v42
	v_mul_f32_e32 v29, v137, v29
	v_mul_f32_e32 v0, v43, v0
	v_mul_f32_e32 v0, v159, v0
	v_add_f32_e32 v42, 1.0, v42
	v_rcp_f32_e32 v42, v42
	s_nop 0
	v_mul_f32_e32 v41, v42, v41
	v_mul_f32_e32 v29, v41, v29
	v_cvt_pk_bf16_f32 v41, v29, v29
	v_ashrrev_i32_e32 v29, 31, v28
	v_lshlrev_b64 v[28:29], 11, v[28:29]
	v_lshl_add_u64 v[26:27], v[26:27], 0, v[28:29]
	s_waitcnt vmcnt(14)
	v_lshlrev_b32_e32 v28, 16, v170
	v_mul_f32_e32 v29, 0xbfb8aa3b, v28
	v_exp_f32_e32 v29, v29
	global_store_short v[26:27], v41, off
	v_add_f32_e32 v29, 1.0, v29
	v_readlane_b32 s0, v252, 0
	v_readlane_b32 s1, v252, 1
	v_rcp_f32_e32 v29, v29
	s_nop 0
	v_mul_f32_e32 v28, v29, v28
	v_mul_f32_e32 v0, v28, v0
	v_cvt_pk_bf16_f32 v0, v0, v0
	global_store_short v[26:27], v0, off offset:128
	s_waitcnt lgkmcnt(0)
	s_barrier
	s_load_dword s0, s[0:1], 0x10
	s_waitcnt lgkmcnt(0)
	s_lshr_b32 s0, s0, 16
	s_cmp_lg_u32 s0, 0
	s_cselect_b64 s[0:1], -1, 0
	s_cmp_lg_u64 s[0:1], 0
	s_addc_u32 s94, s92, 0
	s_cmpk_gt_i32 s94, 0x1ff
	s_cbranch_scc1 .LBB0_1190

.LBB0_1114:
	s_or_b64 exec, exec, s[0:1]
	v_lshlrev_b32_e32 v27, 16, v27
	v_sub_f32_e32 v227, 1.0, v26
	v_lshlrev_b32_e32 v26, 16, v28
	v_mul_f32_e32 v28, 0xbfb8aa3b, v27
	v_exp_f32_e32 v28, v28
	v_add_f32_e32 v0, v0, v176
	v_add_f32_e32 v28, 1.0, v28
	v_rcp_f32_e32 v28, v28
	s_nop 0
	v_mul_f32_e32 v240, v28, v27
	v_lshlrev_b32_e32 v28, 16, v29
	v_mul_f32_e32 v29, 0xbfb8aa3b, v28
	v_exp_f32_e32 v29, v29
	v_sub_f32_e32 v225, 1.0, v41
	v_lshlrev_b32_e32 v27, 16, v171
	v_cvt_pk_bf16_f32 v26, v26, v27
	v_add_f32_e32 v29, 1.0, v29
	v_rcp_f32_e32 v29, v29
	s_nop 0
	v_mul_f32_e32 v244, v29, v28
	v_lshlrev_b32_e32 v29, 16, v173
	v_mul_f32_e32 v41, 0xbfb8aa3b, v29
	v_exp_f32_e32 v41, v41
	v_sub_f32_e32 v241, 1.0, v172
	v_lshlrev_b32_e32 v28, 16, v174
	v_sub_f32_e32 v243, 1.0, v190
	v_add_f32_e32 v41, 1.0, v41
	v_rcp_f32_e32 v41, v41
	s_nop 0
	v_mul_f32_e32 v245, v41, v29
	v_lshlrev_b32_e32 v41, 16, v180
	v_mul_f32_e32 v171, 0xbfb8aa3b, v41
	v_exp_f32_e32 v171, v171
	v_sub_f32_e32 v242, 1.0, v181
	v_lshlrev_b32_e32 v29, 16, v188
	v_cvt_pk_bf16_f32 v27, v28, v29
	v_add_f32_e32 v171, 1.0, v171
	v_rcp_f32_e32 v171, v171
	s_nop 0
	v_mul_f32_e32 v246, v171, v41
	v_lshlrev_b32_e32 v171, 16, v189
	v_mul_f32_e32 v172, 0xbfb8aa3b, v171
	v_exp_f32_e32 v172, v172
	v_lshlrev_b32_e32 v41, 16, v191
	v_sub_f32_e32 v191, 1.0, v192
	v_sub_f32_e32 v192, 1.0, v197
	v_add_f32_e32 v172, 1.0, v172
	v_rcp_f32_e32 v172, v172
	s_nop 0
	v_mul_f32_e32 v247, v172, v171
	v_lshlrev_b32_e32 v172, 16, v193
	v_mul_f32_e32 v173, 0xbfb8aa3b, v172
	v_exp_f32_e32 v173, v173
	v_lshlrev_b32_e32 v171, 16, v194
	v_sub_f32_e32 v193, 1.0, v200
	v_cvt_pk_bf16_f32 v28, v41, v171
	v_add_f32_e32 v173, 1.0, v173
	v_rcp_f32_e32 v173, v173
	s_nop 0
	v_mul_f32_e32 v248, v173, v172
	v_lshlrev_b32_e32 v173, 16, v196
	v_mul_f32_e32 v174, 0xbfb8aa3b, v173
	v_exp_f32_e32 v174, v174
	v_lshlrev_b32_e32 v172, 16, v198
	v_sub_f32_e32 v196, 1.0, v205
	v_add_f32_e32 v174, 1.0, v174
	v_rcp_f32_e32 v174, v174
	s_nop 0
	v_mul_f32_e32 v249, v174, v173
	v_lshlrev_b32_e32 v174, 16, v202
	v_mul_f32_e32 v180, 0xbfb8aa3b, v174
	v_exp_f32_e32 v180, v180
	v_lshlrev_b32_e32 v173, 16, v201
	v_cvt_pk_bf16_f32 v29, v172, v173
	v_add_f32_e32 v180, 1.0, v180
	v_rcp_f32_e32 v180, v180
	s_nop 0
	v_mul_f32_e32 v250, v180, v174
	v_lshlrev_b32_e32 v180, 16, v204
	v_mul_f32_e32 v181, 0xbfb8aa3b, v180
	v_exp_f32_e32 v181, v181
	v_lshlrev_b32_e32 v174, 16, v206
	v_add_f32_e32 v181, 1.0, v181
	v_rcp_f32_e32 v181, v181
	s_nop 0
	v_mul_f32_e32 v251, v181, v180
	v_lshlrev_b32_e32 v181, 16, v207
	v_mul_f32_e32 v188, 0xbfb8aa3b, v181
	v_exp_f32_e32 v188, v188
	v_sub_f32_e32 v197, 1.0, v209
	v_lshlrev_b32_e32 v180, 16, v210
	v_cvt_pk_bf16_f32 v172, v174, v180
	v_add_f32_e32 v188, 1.0, v188
	v_rcp_f32_e32 v188, v188
	s_nop 0
	v_mul_f32_e32 v207, v188, v181
	v_lshlrev_b32_e32 v188, 16, v212
	v_mul_f32_e32 v189, 0xbfb8aa3b, v188
	v_exp_f32_e32 v189, v189
	v_sub_f32_e32 v198, 1.0, v211
	v_lshlrev_b32_e32 v181, 16, v214
	v_add_f32_e32 v189, 1.0, v189
	v_rcp_f32_e32 v189, v189
	s_nop 0
	v_mul_f32_e32 v209, v189, v188
	v_lshlrev_b32_e32 v189, 16, v215
	v_mul_f32_e32 v190, 0xbfb8aa3b, v189
	v_exp_f32_e32 v190, v190
	v_sub_f32_e32 v200, 1.0, v216
	v_lshlrev_b32_e32 v188, 16, v217
	v_cvt_pk_bf16_f32 v173, v181, v188
	v_add_f32_e32 v190, 1.0, v190
	v_rcp_f32_e32 v190, v190
	s_nop 0
	v_mul_f32_e32 v210, v190, v189
	v_lshlrev_b32_e32 v190, 16, v218
	v_mul_f32_e32 v194, 0xbfb8aa3b, v190
	v_exp_f32_e32 v194, v194
	v_sub_f32_e32 v201, 1.0, v219
	v_lshlrev_b32_e32 v189, 16, v220
	v_add_f32_e32 v194, 1.0, v194
	v_rcp_f32_e32 v194, v194
	s_nop 0
	v_mul_f32_e32 v211, v194, v190
	v_lshlrev_b32_e32 v194, 16, v223
	v_mul_f32_e32 v204, 0xbfb8aa3b, v194
	v_exp_f32_e32 v204, v204
	v_sub_f32_e32 v202, 1.0, v222
	v_lshlrev_b32_e32 v190, 16, v224
	v_cvt_pk_bf16_f32 v174, v189, v190
	v_add_f32_e32 v204, 1.0, v204
	v_rcp_f32_e32 v204, v204
	s_nop 0
	v_mul_f32_e32 v212, v204, v194
	v_lshlrev_b32_e32 v204, 16, v226
	v_mul_f32_e32 v206, 0xbfb8aa3b, v204
	v_exp_f32_e32 v206, v206
	v_sub_f32_e32 v205, 1.0, v228
	v_lshlrev_b32_e32 v194, 16, v230
	v_add_f32_e32 v206, 1.0, v206
	s_waitcnt lgkmcnt(0)
	v_lshlrev_b32_e32 v215, 16, v236
	v_mul_f32_e32 v216, 0xbfb8aa3b, v215
	v_exp_f32_e32 v216, v216
	v_rcp_f32_e32 v206, v206
	s_nop 0
	v_mul_f32_e32 v214, v206, v204
	v_sub_f32_e32 v206, 1.0, v232
	v_add_f32_e32 v216, 1.0, v216
	v_lshlrev_b32_e32 v204, 16, v233
	v_rcp_f32_e32 v216, v216
	s_nop 0
	v_mul_f32_e32 v215, v216, v215
	ds_read2st64_b32 v[216:217], v102 offset1:2
	s_waitcnt lgkmcnt(0)
	v_add_f32_e32 v216, v216, v217
	v_mul_f32_e32 v217, 0x3fb8aa3b, v0
	v_exp_f32_e32 v217, v217
	s_nop 0
	v_mul_f32_e32 v217, v240, v217
	v_cvt_pk_bf16_f32 v217, v217, v217
	ds_write_b16 v110, v217
	v_sub_f32_e32 v217, v0, v216
	v_sub_f32_e32 v0, v216, v0
	v_mul_f32_e32 v0, 0x3fb8aa3b, v0
	v_mul_f32_e32 v217, 0x3fb8aa3b, v217
	v_exp_f32_e32 v0, v0
	v_exp_f32_e32 v217, v217
	v_mul_f32_e32 v0, v227, v0
	v_mul_f32_e32 v217, v240, v217
	v_cvt_pk_bf16_f32 v0, v0, v0
	v_cvt_pk_bf16_f32 v217, v217, v217
	ds_write_b16 v110, v0 offset:34816
	v_add_f32_e32 v0, v239, v176
	ds_write_b16 v110, v217 offset:17408
	v_mul_f32_e32 v217, 0x3fb8aa3b, v0
	v_exp_f32_e32 v217, v217
	s_nop 0
	v_mul_f32_e32 v217, v244, v217
	v_cvt_pk_bf16_f32 v217, v217, v217
	ds_write_b16 v110, v217 offset:272
	v_sub_f32_e32 v217, v0, v216
	v_sub_f32_e32 v0, v216, v0
	v_mul_f32_e32 v0, 0x3fb8aa3b, v0
	v_mul_f32_e32 v217, 0x3fb8aa3b, v217
	v_exp_f32_e32 v0, v0
	v_exp_f32_e32 v217, v217
	v_mul_f32_e32 v0, v225, v0
	v_mul_f32_e32 v217, v244, v217
	v_cvt_pk_bf16_f32 v0, v0, v0
	v_cvt_pk_bf16_f32 v217, v217, v217
	ds_write_b16 v110, v0 offset:35088
	v_add_f32_e32 v0, v238, v176
	ds_write_b16 v110, v217 offset:17680
	v_mul_f32_e32 v217, 0x3fb8aa3b, v0
	v_exp_f32_e32 v217, v217
	s_nop 0
	v_mul_f32_e32 v217, v245, v217
	v_cvt_pk_bf16_f32 v217, v217, v217
	ds_write_b16 v110, v217 offset:544
	v_sub_f32_e32 v217, v0, v216
	v_sub_f32_e32 v0, v216, v0
	v_mul_f32_e32 v0, 0x3fb8aa3b, v0
	v_mul_f32_e32 v217, 0x3fb8aa3b, v217
	v_exp_f32_e32 v0, v0
	v_exp_f32_e32 v217, v217
	v_mul_f32_e32 v0, v241, v0
	v_mul_f32_e32 v217, v245, v217
	v_cvt_pk_bf16_f32 v0, v0, v0
	v_cvt_pk_bf16_f32 v217, v217, v217
	ds_write_b16 v110, v0 offset:35360
	v_add_f32_e32 v0, v237, v176
	ds_write_b16 v110, v217 offset:17952
	v_mul_f32_e32 v217, 0x3fb8aa3b, v0
	v_exp_f32_e32 v217, v217
	s_nop 0
	v_mul_f32_e32 v217, v246, v217
	v_cvt_pk_bf16_f32 v217, v217, v217
	ds_write_b16 v110, v217 offset:816
	v_sub_f32_e32 v217, v0, v216
	v_sub_f32_e32 v0, v216, v0
	v_mul_f32_e32 v0, 0x3fb8aa3b, v0
	v_mul_f32_e32 v217, 0x3fb8aa3b, v217
	v_exp_f32_e32 v0, v0
	v_exp_f32_e32 v217, v217
	v_mul_f32_e32 v0, v242, v0
	v_mul_f32_e32 v217, v246, v217
	v_cvt_pk_bf16_f32 v0, v0, v0
	v_cvt_pk_bf16_f32 v217, v217, v217
	ds_write_b16 v110, v0 offset:35632
	v_add_f32_e32 v0, v235, v176
	ds_write_b16 v110, v217 offset:18224
	v_mul_f32_e32 v217, 0x3fb8aa3b, v0
	v_exp_f32_e32 v217, v217
	s_nop 0
	v_mul_f32_e32 v217, v247, v217
	v_cvt_pk_bf16_f32 v217, v217, v217
	ds_write_b16 v110, v217 offset:1088
	v_sub_f32_e32 v217, v0, v216
	v_sub_f32_e32 v0, v216, v0
	v_mul_f32_e32 v0, 0x3fb8aa3b, v0
	v_mul_f32_e32 v217, 0x3fb8aa3b, v217
	v_exp_f32_e32 v0, v0
	v_exp_f32_e32 v217, v217
	v_mul_f32_e32 v0, v243, v0
	v_mul_f32_e32 v217, v247, v217
	v_cvt_pk_bf16_f32 v0, v0, v0
	v_cvt_pk_bf16_f32 v217, v217, v217
	ds_write_b16 v110, v0 offset:35904
	v_add_f32_e32 v0, v234, v176
	ds_write_b16 v110, v217 offset:18496
	v_mul_f32_e32 v217, 0x3fb8aa3b, v0
	v_exp_f32_e32 v217, v217
	s_nop 0
	v_mul_f32_e32 v217, v248, v217
	v_cvt_pk_bf16_f32 v217, v217, v217
	ds_write_b16 v110, v217 offset:1360
	v_sub_f32_e32 v217, v0, v216
	v_sub_f32_e32 v0, v216, v0
	v_mul_f32_e32 v0, 0x3fb8aa3b, v0
	v_exp_f32_e32 v0, v0
	v_mul_f32_e32 v217, 0x3fb8aa3b, v217
	v_exp_f32_e32 v217, v217
	v_mul_f32_e32 v0, v191, v0
	v_cvt_pk_bf16_f32 v0, v0, v0
	ds_write_b16 v110, v0 offset:36176
	v_add_f32_e32 v0, v231, v176
	v_mul_f32_e32 v191, 0x3fb8aa3b, v0
	v_exp_f32_e32 v191, v191
	v_mul_f32_e32 v217, v248, v217
	v_cvt_pk_bf16_f32 v217, v217, v217
	ds_write_b16 v110, v217 offset:18768
	v_mul_f32_e32 v191, v249, v191
	v_cvt_pk_bf16_f32 v191, v191, v191
	ds_write_b16 v110, v191 offset:1632
	v_sub_f32_e32 v191, v0, v216
	v_sub_f32_e32 v0, v216, v0
	v_mul_f32_e32 v0, 0x3fb8aa3b, v0
	v_mul_f32_e32 v191, 0x3fb8aa3b, v191
	v_exp_f32_e32 v0, v0
	v_exp_f32_e32 v191, v191
	v_mul_f32_e32 v0, v192, v0
	v_mul_f32_e32 v191, v249, v191
	v_cvt_pk_bf16_f32 v0, v0, v0
	v_cvt_pk_bf16_f32 v191, v191, v191
	ds_write_b16 v110, v0 offset:36448
	v_add_f32_e32 v0, v229, v176
	ds_write_b16 v110, v191 offset:19040
	v_mul_f32_e32 v191, 0x3fb8aa3b, v0
	v_exp_f32_e32 v191, v191
	s_nop 0
	v_mul_f32_e32 v191, v250, v191
	v_cvt_pk_bf16_f32 v191, v191, v191
	ds_write_b16 v110, v191 offset:1904
	v_sub_f32_e32 v191, v0, v216
	v_sub_f32_e32 v0, v216, v0
	v_mul_f32_e32 v0, 0x3fb8aa3b, v0
	v_mul_f32_e32 v191, 0x3fb8aa3b, v191
	v_exp_f32_e32 v0, v0
	v_exp_f32_e32 v191, v191
	v_mul_f32_e32 v0, v193, v0
	v_mul_f32_e32 v191, v250, v191
	v_cvt_pk_bf16_f32 v0, v0, v0
	v_cvt_pk_bf16_f32 v191, v191, v191
	ds_write_b16 v110, v0 offset:36720
	v_add_f32_e32 v0, v221, v176
	ds_write_b16 v110, v191 offset:19312
	v_mul_f32_e32 v191, 0x3fb8aa3b, v0
	v_exp_f32_e32 v191, v191
	s_nop 0
	v_mul_f32_e32 v191, v251, v191
	v_cvt_pk_bf16_f32 v191, v191, v191
	ds_write_b16 v110, v191 offset:2176
	v_sub_f32_e32 v191, v0, v216
	v_sub_f32_e32 v0, v216, v0
	v_mul_f32_e32 v0, 0x3fb8aa3b, v0
	v_mul_f32_e32 v191, 0x3fb8aa3b, v191
	v_exp_f32_e32 v0, v0
	v_exp_f32_e32 v191, v191
	v_mul_f32_e32 v0, v196, v0
	v_mul_f32_e32 v191, v251, v191
	v_cvt_pk_bf16_f32 v0, v0, v0
	v_cvt_pk_bf16_f32 v191, v191, v191
	ds_write_b16 v110, v0 offset:36992
	v_add_f32_e32 v0, v213, v176
	ds_write_b16 v110, v191 offset:19584
	v_mul_f32_e32 v191, 0x3fb8aa3b, v0
	v_exp_f32_e32 v191, v191
	s_nop 0
	v_mul_f32_e32 v191, v207, v191
	v_cvt_pk_bf16_f32 v191, v191, v191
	ds_write_b16 v110, v191 offset:2448
	v_sub_f32_e32 v191, v0, v216
	v_sub_f32_e32 v0, v216, v0
	v_mul_f32_e32 v0, 0x3fb8aa3b, v0
	v_mul_f32_e32 v191, 0x3fb8aa3b, v191
	v_exp_f32_e32 v0, v0
	v_exp_f32_e32 v191, v191
	v_mul_f32_e32 v0, v197, v0
	v_mul_f32_e32 v191, v207, v191
	v_cvt_pk_bf16_f32 v0, v0, v0
	v_cvt_pk_bf16_f32 v191, v191, v191
	ds_write_b16 v110, v0 offset:37264
	v_add_f32_e32 v0, v208, v176
	ds_write_b16 v110, v191 offset:19856
	v_mul_f32_e32 v191, 0x3fb8aa3b, v0
	v_exp_f32_e32 v191, v191
	s_nop 0
	v_mul_f32_e32 v191, v209, v191
	v_cvt_pk_bf16_f32 v191, v191, v191
	ds_write_b16 v110, v191 offset:2720
	v_sub_f32_e32 v191, v0, v216
	v_sub_f32_e32 v0, v216, v0
	v_mul_f32_e32 v0, 0x3fb8aa3b, v0
	v_mul_f32_e32 v191, 0x3fb8aa3b, v191
	v_exp_f32_e32 v0, v0
	v_exp_f32_e32 v191, v191
	v_mul_f32_e32 v0, v198, v0
	v_mul_f32_e32 v191, v209, v191
	v_cvt_pk_bf16_f32 v0, v0, v0
	v_cvt_pk_bf16_f32 v191, v191, v191
	ds_write_b16 v110, v0 offset:37536
	v_add_f32_e32 v0, v203, v176
	ds_write_b16 v110, v191 offset:20128
	v_mul_f32_e32 v191, 0x3fb8aa3b, v0
	v_exp_f32_e32 v191, v191
	s_nop 0
	v_mul_f32_e32 v191, v210, v191
	v_cvt_pk_bf16_f32 v191, v191, v191
	ds_write_b16 v110, v191 offset:2992
	v_sub_f32_e32 v191, v0, v216
	v_sub_f32_e32 v0, v216, v0
	v_mul_f32_e32 v0, 0x3fb8aa3b, v0
	v_mul_f32_e32 v191, 0x3fb8aa3b, v191
	v_exp_f32_e32 v0, v0
	v_exp_f32_e32 v191, v191
	v_mul_f32_e32 v0, v200, v0
	v_mul_f32_e32 v191, v210, v191
	v_cvt_pk_bf16_f32 v0, v0, v0
	v_cvt_pk_bf16_f32 v191, v191, v191
	ds_write_b16 v110, v0 offset:37808
	v_add_f32_e32 v0, v199, v176
	ds_write_b16 v110, v191 offset:20400
	v_mul_f32_e32 v191, 0x3fb8aa3b, v0
	v_exp_f32_e32 v191, v191
	s_nop 0
	v_mul_f32_e32 v191, v211, v191
	v_cvt_pk_bf16_f32 v191, v191, v191
	ds_write_b16 v110, v191 offset:3264
	v_sub_f32_e32 v191, v0, v216
	v_sub_f32_e32 v0, v216, v0
	v_mul_f32_e32 v0, 0x3fb8aa3b, v0
	v_mul_f32_e32 v191, 0x3fb8aa3b, v191
	v_exp_f32_e32 v0, v0
	v_exp_f32_e32 v191, v191
	v_mul_f32_e32 v0, v201, v0
	v_mul_f32_e32 v191, v211, v191
	v_cvt_pk_bf16_f32 v0, v0, v0
	v_cvt_pk_bf16_f32 v191, v191, v191
	ds_write_b16 v110, v0 offset:38080
	v_add_f32_e32 v0, v195, v176
	ds_write_b16 v110, v191 offset:20672
	v_mul_f32_e32 v191, 0x3fb8aa3b, v0
	v_exp_f32_e32 v191, v191
	s_nop 0
	v_mul_f32_e32 v191, v212, v191
	v_cvt_pk_bf16_f32 v191, v191, v191
	ds_write_b16 v110, v191 offset:3536
	v_sub_f32_e32 v191, v0, v216
	v_sub_f32_e32 v0, v216, v0
	v_mul_f32_e32 v0, 0x3fb8aa3b, v0
	v_exp_f32_e32 v0, v0
	v_mul_f32_e32 v191, 0x3fb8aa3b, v191
	v_exp_f32_e32 v191, v191
	v_mul_f32_e32 v0, v202, v0
	v_cvt_pk_bf16_f32 v0, v0, v0
	ds_write_b16 v110, v0 offset:38352
	v_add_f32_e32 v0, v178, v176
	v_mul_f32_e32 v178, 0x3fb8aa3b, v0
	v_exp_f32_e32 v178, v178
	v_mul_f32_e32 v191, v212, v191
	v_cvt_pk_bf16_f32 v191, v191, v191
	ds_write_b16 v110, v191 offset:20944
	v_mul_f32_e32 v178, v214, v178
	v_cvt_pk_bf16_f32 v178, v178, v178
	ds_write_b16 v110, v178 offset:3808
	v_sub_f32_e32 v178, v0, v216
	v_sub_f32_e32 v0, v216, v0
	v_mul_f32_e32 v0, 0x3fb8aa3b, v0
	v_exp_f32_e32 v0, v0
	v_mul_f32_e32 v178, 0x3fb8aa3b, v178
	v_exp_f32_e32 v178, v178
	v_mul_f32_e32 v0, v205, v0
	v_cvt_pk_bf16_f32 v0, v0, v0
	ds_write_b16 v110, v0 offset:38624
	v_add_f32_e32 v0, v175, v176
	v_mul_f32_e32 v175, 0x3fb8aa3b, v0
	v_exp_f32_e32 v175, v175
	v_mul_f32_e32 v178, v214, v178
	v_cvt_pk_bf16_f32 v178, v178, v178
	ds_write_b16 v110, v178 offset:21216
	v_mul_f32_e32 v175, v215, v175
	v_cvt_pk_bf16_f32 v175, v175, v175
	ds_write_b16 v110, v175 offset:4080
	v_sub_f32_e32 v175, v0, v216
	v_mul_f32_e32 v175, 0x3fb8aa3b, v175
	v_sub_f32_e32 v0, v216, v0
	v_exp_f32_e32 v175, v175
	v_mul_f32_e32 v0, 0x3fb8aa3b, v0
	v_exp_f32_e32 v0, v0
	v_mul_f32_e32 v175, v215, v175
	v_cvt_pk_bf16_f32 v175, v175, v175
	v_mul_f32_e32 v0, v206, v0
	ds_write_b16 v110, v175 offset:21488
	v_cvt_pk_bf16_f32 v0, v0, v0
	ds_write_b16 v110, v0 offset:38896
	v_cvt_pk_bf16_f32 v175, v194, v204
	ds_write_b128 v144, v[26:29] offset:52224
	ds_write_b128 v144, v[172:175] offset:52240
	s_and_saveexec_b64 s[0:1], s[36:37]
	s_cbranch_execz .LBB0_1117
	s_or_b32 s24, s10, s28
	v_readlane_b32 s25, v255, 20
	s_lshl_b32 s88, s24, s25
	s_and_b64 s[24:25], s[86:87], exec
	s_cselect_b32 s24, s95, s33
	s_add_i32 s24, s88, s24
	s_ashr_i32 s25, s24, 31
	v_readlane_b32 s40, v252, 51
	s_lshl_b64 s[24:25], s[24:25], 16
	v_readlane_b32 s54, v253, 1
	v_readlane_b32 s55, v253, 2
	s_add_u32 s88, s54, s24
	s_addc_u32 s89, s55, s25
	s_mov_b64 s[24:25], 0
	v_mov_b32_e32 v26, v100
	v_mov_b32_e32 v27, v30
	v_readlane_b32 s41, v252, 52
	v_readlane_b32 s42, v252, 53
	v_readlane_b32 s43, v252, 54
	v_readlane_b32 s44, v252, 55
	v_readlane_b32 s45, v252, 56
	v_readlane_b32 s46, v252, 57
	v_readlane_b32 s47, v252, 58
	v_readlane_b32 s48, v252, 59
	v_readlane_b32 s49, v252, 60
	v_readlane_b32 s50, v252, 61
	v_readlane_b32 s51, v252, 62
	v_readlane_b32 s52, v252, 63
	v_readlane_b32 s53, v253, 0
